# speedup vs baseline: 1.0031x; 1.0031x over previous
.LBB0_103:
	s_lshl_b32 s10, s10, 6
	s_and_b32 s22, s22, 0x60
	s_and_b32 s10, s10, 0xffffff00
	s_or_b32 s10, s10, s22
	s_waitcnt lgkmcnt(0)
	v_or_b32_e32 v38, s10, v1
	ds_read2_b32 v[26:27], v3 offset1:33
	v_ashrrev_i32_e32 v39, 31, v38
	s_waitcnt lgkmcnt(0)
	v_cvt_pk_bf16_f32 v26, v26, v27
	ds_read2_b32 v[28:29], v3 offset0:66 offset1:99
	v_lshl_add_u64 v[30:31], s[24:25], 1, v[10:11]
	v_lshlrev_b64 v[38:39], 11, v[38:39]
	s_waitcnt lgkmcnt(0)
	v_cvt_pk_bf16_f32 v27, v28, v29
	ds_read2_b32 v[28:29], v3 offset0:132 offset1:165
	v_lshl_add_u64 v[38:39], v[30:31], 0, v[38:39]
	s_waitcnt lgkmcnt(0)
	v_cvt_pk_bf16_f32 v28, v28, v29
	ds_read2_b32 v[32:33], v3 offset0:198 offset1:231
	s_waitcnt lgkmcnt(0)
	v_cvt_pk_bf16_f32 v29, v32, v33
	flat_store_dwordx4 v[38:39], v[26:29] sc1
	v_or_b32_e32 v38, s10, v9
	ds_read2_b32 v[26:27], v3 offset0:8 offset1:41
	v_ashrrev_i32_e32 v39, 31, v38
	s_waitcnt lgkmcnt(0)
	v_cvt_pk_bf16_f32 v26, v26, v27
	ds_read2_b32 v[28:29], v3 offset0:74 offset1:107
	v_lshlrev_b64 v[38:39], 11, v[38:39]
	s_waitcnt lgkmcnt(0)
	v_cvt_pk_bf16_f32 v27, v28, v29
	ds_read2_b32 v[28:29], v3 offset0:140 offset1:173
	v_lshl_add_u64 v[38:39], v[30:31], 0, v[38:39]
	s_waitcnt lgkmcnt(0)
	v_cvt_pk_bf16_f32 v28, v28, v29
	ds_read2_b32 v[32:33], v3 offset0:206 offset1:239
	s_waitcnt lgkmcnt(0)
	v_cvt_pk_bf16_f32 v29, v32, v33
	flat_store_dwordx4 v[38:39], v[26:29] sc1
	v_or_b32_e32 v38, s10, v34
	ds_read2_b32 v[26:27], v3 offset0:16 offset1:49
	v_ashrrev_i32_e32 v39, 31, v38
	s_waitcnt lgkmcnt(0)
	v_cvt_pk_bf16_f32 v26, v26, v27
	ds_read2_b32 v[28:29], v3 offset0:82 offset1:115
	v_lshlrev_b64 v[38:39], 11, v[38:39]
	s_waitcnt lgkmcnt(0)
	v_cvt_pk_bf16_f32 v27, v28, v29
	ds_read2_b32 v[28:29], v3 offset0:148 offset1:181
	v_lshl_add_u64 v[38:39], v[30:31], 0, v[38:39]
	s_waitcnt lgkmcnt(0)
	v_cvt_pk_bf16_f32 v28, v28, v29
	ds_read2_b32 v[32:33], v3 offset0:214 offset1:247
	s_waitcnt lgkmcnt(0)
	v_cvt_pk_bf16_f32 v29, v32, v33
	flat_store_dwordx4 v[38:39], v[26:29] sc1
	v_or_b32_e32 v38, s10, v35
	ds_read2_b32 v[26:27], v3 offset0:24 offset1:57
	v_ashrrev_i32_e32 v39, 31, v38
	s_waitcnt lgkmcnt(0)
	v_cvt_pk_bf16_f32 v26, v26, v27
	ds_read2_b32 v[28:29], v3 offset0:90 offset1:123
	v_lshlrev_b64 v[38:39], 11, v[38:39]
	s_waitcnt lgkmcnt(0)
	v_cvt_pk_bf16_f32 v27, v28, v29
	ds_read2_b32 v[28:29], v3 offset0:156 offset1:189
	v_lshl_add_u64 v[30:31], v[30:31], 0, v[38:39]
	s_waitcnt lgkmcnt(0)
	v_cvt_pk_bf16_f32 v28, v28, v29
	ds_read2_b32 v[32:33], v3 offset0:222 offset1:255
	s_waitcnt lgkmcnt(0)
	v_cvt_pk_bf16_f32 v29, v32, v33
	flat_store_dwordx4 v[30:31], v[26:29] sc1
	s_waitcnt lgkmcnt(0)
	s_mov_b32 s33, s59
	s_andn2_b64 vcc, exec, s[8:9]
	s_mov_b64 s[8:9], -1
	s_cbranch_vccz .LBB0_31

.LBB0_143:
	s_lshl_b32 s10, s10, 6
	s_and_b32 s22, s22, 0x60
	s_and_b32 s10, s10, 0xffffff00
	s_or_b32 s10, s22, s10
	s_bitset1_b32 s10, 7
	s_waitcnt lgkmcnt(0)
	v_or_b32_e32 v38, s10, v1
	ds_read2_b32 v[26:27], v3 offset1:33
	v_ashrrev_i32_e32 v39, 31, v38
	s_waitcnt lgkmcnt(0)
	v_cvt_pk_bf16_f32 v26, v26, v27
	ds_read2_b32 v[28:29], v3 offset0:66 offset1:99
	v_lshl_add_u64 v[30:31], s[24:25], 1, v[10:11]
	v_lshlrev_b64 v[38:39], 11, v[38:39]
	s_waitcnt lgkmcnt(0)
	v_cvt_pk_bf16_f32 v27, v28, v29
	ds_read2_b32 v[28:29], v3 offset0:132 offset1:165
	v_lshl_add_u64 v[38:39], v[30:31], 0, v[38:39]
	s_waitcnt lgkmcnt(0)
	v_cvt_pk_bf16_f32 v28, v28, v29
	ds_read2_b32 v[32:33], v3 offset0:198 offset1:231
	s_waitcnt lgkmcnt(0)
	v_cvt_pk_bf16_f32 v29, v32, v33
	flat_store_dwordx4 v[38:39], v[26:29] sc1
	v_or_b32_e32 v38, s10, v9
	ds_read2_b32 v[26:27], v3 offset0:8 offset1:41
	v_ashrrev_i32_e32 v39, 31, v38
	s_waitcnt lgkmcnt(0)
	v_cvt_pk_bf16_f32 v26, v26, v27
	ds_read2_b32 v[28:29], v3 offset0:74 offset1:107
	v_lshlrev_b64 v[38:39], 11, v[38:39]
	s_waitcnt lgkmcnt(0)
	v_cvt_pk_bf16_f32 v27, v28, v29
	ds_read2_b32 v[28:29], v3 offset0:140 offset1:173
	v_lshl_add_u64 v[38:39], v[30:31], 0, v[38:39]
	s_waitcnt lgkmcnt(0)
	v_cvt_pk_bf16_f32 v28, v28, v29
	ds_read2_b32 v[32:33], v3 offset0:206 offset1:239
	s_waitcnt lgkmcnt(0)
	v_cvt_pk_bf16_f32 v29, v32, v33
	flat_store_dwordx4 v[38:39], v[26:29] sc1
	v_or_b32_e32 v38, s10, v34
	ds_read2_b32 v[26:27], v3 offset0:16 offset1:49
	v_ashrrev_i32_e32 v39, 31, v38
	s_waitcnt lgkmcnt(0)
	v_cvt_pk_bf16_f32 v26, v26, v27
	ds_read2_b32 v[28:29], v3 offset0:82 offset1:115
	v_lshlrev_b64 v[38:39], 11, v[38:39]
	s_waitcnt lgkmcnt(0)
	v_cvt_pk_bf16_f32 v27, v28, v29
	ds_read2_b32 v[28:29], v3 offset0:148 offset1:181
	v_lshl_add_u64 v[38:39], v[30:31], 0, v[38:39]
	s_waitcnt lgkmcnt(0)
	v_cvt_pk_bf16_f32 v28, v28, v29
	ds_read2_b32 v[32:33], v3 offset0:214 offset1:247
	s_waitcnt lgkmcnt(0)
	v_cvt_pk_bf16_f32 v29, v32, v33
	flat_store_dwordx4 v[38:39], v[26:29] sc1
	v_or_b32_e32 v38, s10, v35
	ds_read2_b32 v[26:27], v3 offset0:24 offset1:57
	v_ashrrev_i32_e32 v39, 31, v38
	s_waitcnt lgkmcnt(0)
	v_cvt_pk_bf16_f32 v26, v26, v27
	ds_read2_b32 v[28:29], v3 offset0:90 offset1:123
	v_lshlrev_b64 v[38:39], 11, v[38:39]
	s_waitcnt lgkmcnt(0)
	v_cvt_pk_bf16_f32 v27, v28, v29
	ds_read2_b32 v[28:29], v3 offset0:156 offset1:189
	v_lshl_add_u64 v[30:31], v[30:31], 0, v[38:39]
	s_waitcnt lgkmcnt(0)
	v_cvt_pk_bf16_f32 v28, v28, v29
	ds_read2_b32 v[32:33], v3 offset0:222 offset1:255
	s_waitcnt lgkmcnt(0)
	v_cvt_pk_bf16_f32 v29, v32, v33
	flat_store_dwordx4 v[30:31], v[26:29] sc1
	s_waitcnt lgkmcnt(0)
	s_mov_b64 s[22:23], -1
	s_mov_b32 s10, s33

.LBB0_149:
	v_add_u32_e32 v30, s9, v4
	v_ashrrev_i32_e32 v31, 31, v30
	v_lshlrev_b64 v[32:33], 12, v[30:31]
	v_lshl_add_u64 v[32:33], v[26:27], 0, v[32:33]
	global_load_dword v184, v[32:33], off
	v_add_u32_e32 v32, 2, v30
	v_ashrrev_i32_e32 v33, 31, v32
	v_lshlrev_b64 v[32:33], 12, v[32:33]
	v_lshl_add_u64 v[32:33], v[26:27], 0, v[32:33]
	s_add_i32 s9, s9, 32
	s_cmp_lg_u32 s9, 64
	global_load_dword v185, v[32:33], off
	v_add_u32_e32 v32, 4, v30
	v_ashrrev_i32_e32 v33, 31, v32
	v_lshlrev_b64 v[32:33], 12, v[32:33]
	v_lshl_add_u64 v[32:33], v[26:27], 0, v[32:33]
	global_load_dword v186, v[32:33], off
	v_add_u32_e32 v32, 6, v30
	v_ashrrev_i32_e32 v33, 31, v32
	v_lshlrev_b64 v[32:33], 12, v[32:33]
	v_lshl_add_u64 v[32:33], v[26:27], 0, v[32:33]
	global_load_dword v187, v[32:33], off
	v_add_u32_e32 v32, 8, v30
	v_ashrrev_i32_e32 v33, 31, v32
	v_lshlrev_b64 v[32:33], 12, v[32:33]
	v_lshl_add_u64 v[32:33], v[26:27], 0, v[32:33]
	global_load_dword v188, v[32:33], off
	v_add_u32_e32 v32, 10, v30
	v_ashrrev_i32_e32 v33, 31, v32
	v_lshlrev_b64 v[32:33], 12, v[32:33]
	v_lshl_add_u64 v[32:33], v[26:27], 0, v[32:33]
	global_load_dword v189, v[32:33], off
	v_add_u32_e32 v32, 12, v30
	v_ashrrev_i32_e32 v33, 31, v32
	v_lshlrev_b64 v[32:33], 12, v[32:33]
	v_lshl_add_u64 v[32:33], v[26:27], 0, v[32:33]
	global_load_dword v190, v[32:33], off
	v_add_u32_e32 v32, 14, v30
	v_ashrrev_i32_e32 v33, 31, v32
	v_lshlrev_b64 v[32:33], 12, v[32:33]
	v_lshl_add_u64 v[32:33], v[26:27], 0, v[32:33]
	global_load_dword v191, v[32:33], off
	v_add_u32_e32 v32, 16, v30
	v_ashrrev_i32_e32 v33, 31, v32
	v_lshlrev_b64 v[32:33], 12, v[32:33]
	v_lshl_add_u64 v[32:33], v[26:27], 0, v[32:33]
	global_load_dword v192, v[32:33], off
	v_add_u32_e32 v32, 18, v30
	v_ashrrev_i32_e32 v33, 31, v32
	v_lshlrev_b64 v[32:33], 12, v[32:33]
	v_lshl_add_u64 v[32:33], v[26:27], 0, v[32:33]
	global_load_dword v193, v[32:33], off
	v_add_u32_e32 v32, 20, v30
	v_ashrrev_i32_e32 v33, 31, v32
	v_lshlrev_b64 v[32:33], 12, v[32:33]
	v_lshl_add_u64 v[32:33], v[26:27], 0, v[32:33]
	global_load_dword v194, v[32:33], off
	v_add_u32_e32 v32, 22, v30
	v_ashrrev_i32_e32 v33, 31, v32
	v_lshlrev_b64 v[32:33], 12, v[32:33]
	v_lshl_add_u64 v[32:33], v[26:27], 0, v[32:33]
	global_load_dword v195, v[32:33], off
	v_add_u32_e32 v32, 24, v30
	v_ashrrev_i32_e32 v33, 31, v32
	v_lshlrev_b64 v[32:33], 12, v[32:33]
	v_lshl_add_u64 v[32:33], v[26:27], 0, v[32:33]
	global_load_dword v196, v[32:33], off
	v_add_u32_e32 v32, 26, v30
	v_ashrrev_i32_e32 v33, 31, v32
	v_lshlrev_b64 v[32:33], 12, v[32:33]
	v_lshl_add_u64 v[32:33], v[26:27], 0, v[32:33]
	global_load_dword v197, v[32:33], off
	v_add_u32_e32 v32, 28, v30
	v_ashrrev_i32_e32 v33, 31, v32
	v_lshlrev_b64 v[32:33], 12, v[32:33]
	v_lshl_add_u64 v[32:33], v[26:27], 0, v[32:33]
	v_add_u32_e32 v30, 30, v30
	v_ashrrev_i32_e32 v31, 31, v30
	v_lshlrev_b64 v[30:31], 12, v[30:31]
	v_lshl_add_u64 v[30:31], v[26:27], 0, v[30:31]
	global_load_dword v198, v[32:33], off
	global_load_dword v199, v[30:31], off
	s_waitcnt vmcnt(0)
	ds_write_b32 v28, v184
	ds_write_b32 v28, v185 offset:264
	ds_write_b32 v28, v186 offset:528
	ds_write_b32 v28, v187 offset:792
	ds_write_b32 v28, v188 offset:1056
	ds_write_b32 v28, v189 offset:1320
	ds_write_b32 v28, v190 offset:1584
	ds_write_b32 v28, v191 offset:1848
	ds_write_b32 v28, v192 offset:2112
	ds_write_b32 v28, v193 offset:2376
	ds_write_b32 v28, v194 offset:2640
	ds_write_b32 v28, v195 offset:2904
	ds_write_b32 v28, v196 offset:3168
	ds_write_b32 v28, v197 offset:3432
	ds_write_b32 v28, v198 offset:3696
	ds_write_b32 v28, v199 offset:3960
	v_add_u32_e32 v28, 0x1080, v28
	s_cbranch_scc1 .LBB0_149
	s_waitcnt lgkmcnt(0)
	ds_read2_b32 v[26:27], v3 offset1:33
	s_ashr_i32 s23, s22, 31
	s_waitcnt lgkmcnt(0)
	v_cvt_pk_bf16_f32 v26, v26, v27
	ds_read2_b32 v[28:29], v3 offset0:66 offset1:99
	v_or_b32_e32 v4, s8, v1
	v_lshl_add_u64 v[32:33], s[22:23], 1, v[12:13]
	s_waitcnt lgkmcnt(0)
	v_cvt_pk_bf16_f32 v27, v28, v29
	ds_read2_b32 v[28:29], v3 offset0:132 offset1:165
	v_mad_i64_i32 v[38:39], s[22:23], v4, s46, v[32:33]
	s_waitcnt lgkmcnt(0)
	v_cvt_pk_bf16_f32 v28, v28, v29
	ds_read2_b32 v[30:31], v3 offset0:198 offset1:231
	s_waitcnt lgkmcnt(0)
	v_cvt_pk_bf16_f32 v29, v30, v31
	flat_store_dwordx4 v[38:39], v[26:29] sc1
	ds_read2_b32 v[26:27], v3 offset0:8 offset1:41
	v_or_b32_e32 v4, s8, v9
	s_waitcnt lgkmcnt(0)
	v_cvt_pk_bf16_f32 v26, v26, v27
	ds_read2_b32 v[28:29], v3 offset0:74 offset1:107
	s_waitcnt lgkmcnt(0)
	v_cvt_pk_bf16_f32 v27, v28, v29
	ds_read2_b32 v[28:29], v3 offset0:140 offset1:173
	v_mad_i64_i32 v[38:39], s[22:23], v4, s46, v[32:33]
	s_waitcnt lgkmcnt(0)
	v_cvt_pk_bf16_f32 v28, v28, v29
	ds_read2_b32 v[30:31], v3 offset0:206 offset1:239
	s_waitcnt lgkmcnt(0)
	v_cvt_pk_bf16_f32 v29, v30, v31
	flat_store_dwordx4 v[38:39], v[26:29] sc1
	ds_read2_b32 v[26:27], v3 offset0:16 offset1:49
	v_or_b32_e32 v4, s8, v34
	s_waitcnt lgkmcnt(0)
	v_cvt_pk_bf16_f32 v26, v26, v27
	ds_read2_b32 v[28:29], v3 offset0:82 offset1:115
	s_waitcnt lgkmcnt(0)
	v_cvt_pk_bf16_f32 v27, v28, v29
	ds_read2_b32 v[28:29], v3 offset0:148 offset1:181
	v_mad_i64_i32 v[38:39], s[22:23], v4, s46, v[32:33]
	s_waitcnt lgkmcnt(0)
	v_cvt_pk_bf16_f32 v28, v28, v29
	ds_read2_b32 v[30:31], v3 offset0:214 offset1:247
	s_waitcnt lgkmcnt(0)
	v_cvt_pk_bf16_f32 v29, v30, v31
	flat_store_dwordx4 v[38:39], v[26:29] sc1
	ds_read2_b32 v[26:27], v3 offset0:24 offset1:57
	v_or_b32_e32 v4, s8, v35
	s_waitcnt lgkmcnt(0)
	v_cvt_pk_bf16_f32 v26, v26, v27
	ds_read2_b32 v[28:29], v3 offset0:90 offset1:123
	s_waitcnt lgkmcnt(0)
	v_cvt_pk_bf16_f32 v27, v28, v29
	ds_read2_b32 v[28:29], v3 offset0:156 offset1:189
	s_waitcnt lgkmcnt(0)
	v_cvt_pk_bf16_f32 v28, v28, v29
	ds_read2_b32 v[30:31], v3 offset0:222 offset1:255
	s_waitcnt lgkmcnt(0)
	v_cvt_pk_bf16_f32 v29, v30, v31
	v_mad_i64_i32 v[30:31], s[8:9], v4, s46, v[32:33]
	flat_store_dwordx4 v[30:31], v[26:29] sc1
	s_waitcnt lgkmcnt(0)
	s_mov_b64 s[8:9], -1
	s_mov_b32 s10, s33

.LBB0_153:
	s_waitcnt lgkmcnt(0)
	v_or_b32_e32 v38, s24, v1
	ds_read2_b32 v[26:27], v3 offset1:33
	v_ashrrev_i32_e32 v39, 31, v38
	s_waitcnt lgkmcnt(0)
	v_cvt_pk_bf16_f32 v26, v26, v27
	ds_read2_b32 v[28:29], v3 offset0:66 offset1:99
	v_lshl_add_u64 v[30:31], s[28:29], 1, v[14:15]
	v_lshlrev_b64 v[38:39], 11, v[38:39]
	s_waitcnt lgkmcnt(0)
	v_cvt_pk_bf16_f32 v27, v28, v29
	ds_read2_b32 v[28:29], v3 offset0:132 offset1:165
	v_lshl_add_u64 v[38:39], v[30:31], 0, v[38:39]
	s_waitcnt lgkmcnt(0)
	v_cvt_pk_bf16_f32 v28, v28, v29
	ds_read2_b32 v[32:33], v3 offset0:198 offset1:231
	s_waitcnt lgkmcnt(0)
	v_cvt_pk_bf16_f32 v29, v32, v33
	flat_store_dwordx4 v[38:39], v[26:29] sc1
	v_or_b32_e32 v38, s24, v9
	ds_read2_b32 v[26:27], v3 offset0:8 offset1:41
	v_ashrrev_i32_e32 v39, 31, v38
	s_waitcnt lgkmcnt(0)
	v_cvt_pk_bf16_f32 v26, v26, v27
	ds_read2_b32 v[28:29], v3 offset0:74 offset1:107
	v_lshlrev_b64 v[38:39], 11, v[38:39]
	s_waitcnt lgkmcnt(0)
	v_cvt_pk_bf16_f32 v27, v28, v29
	ds_read2_b32 v[28:29], v3 offset0:140 offset1:173
	v_lshl_add_u64 v[38:39], v[30:31], 0, v[38:39]
	s_waitcnt lgkmcnt(0)
	v_cvt_pk_bf16_f32 v28, v28, v29
	ds_read2_b32 v[32:33], v3 offset0:206 offset1:239
	s_waitcnt lgkmcnt(0)
	v_cvt_pk_bf16_f32 v29, v32, v33
	flat_store_dwordx4 v[38:39], v[26:29] sc1
	v_or_b32_e32 v38, s24, v34
	ds_read2_b32 v[26:27], v3 offset0:16 offset1:49
	v_ashrrev_i32_e32 v39, 31, v38
	s_waitcnt lgkmcnt(0)
	v_cvt_pk_bf16_f32 v26, v26, v27
	ds_read2_b32 v[28:29], v3 offset0:82 offset1:115
	v_lshlrev_b64 v[38:39], 11, v[38:39]
	s_waitcnt lgkmcnt(0)
	v_cvt_pk_bf16_f32 v27, v28, v29
	ds_read2_b32 v[28:29], v3 offset0:148 offset1:181
	v_lshl_add_u64 v[38:39], v[30:31], 0, v[38:39]
	s_waitcnt lgkmcnt(0)
	v_cvt_pk_bf16_f32 v28, v28, v29
	ds_read2_b32 v[32:33], v3 offset0:214 offset1:247
	s_waitcnt lgkmcnt(0)
	v_cvt_pk_bf16_f32 v29, v32, v33
	flat_store_dwordx4 v[38:39], v[26:29] sc1
	v_or_b32_e32 v38, s24, v35
	ds_read2_b32 v[26:27], v3 offset0:24 offset1:57
	v_ashrrev_i32_e32 v39, 31, v38
	s_waitcnt lgkmcnt(0)
	v_cvt_pk_bf16_f32 v26, v26, v27
	ds_read2_b32 v[28:29], v3 offset0:90 offset1:123
	v_lshlrev_b64 v[38:39], 11, v[38:39]
	s_waitcnt lgkmcnt(0)
	v_cvt_pk_bf16_f32 v27, v28, v29
	ds_read2_b32 v[28:29], v3 offset0:156 offset1:189
	v_lshl_add_u64 v[30:31], v[30:31], 0, v[38:39]
	s_waitcnt lgkmcnt(0)
	v_cvt_pk_bf16_f32 v28, v28, v29
	ds_read2_b32 v[32:33], v3 offset0:222 offset1:255
	s_waitcnt lgkmcnt(0)
	v_cvt_pk_bf16_f32 v29, v32, v33
	flat_store_dwordx4 v[30:31], v[26:29] sc1
	s_waitcnt lgkmcnt(0)
	s_mov_b64 s[8:9], -1
	s_mov_b32 s10, s33

.LBB0_159:
	v_add_u32_e32 v30, s9, v4
	v_ashrrev_i32_e32 v31, 31, v30
	v_lshlrev_b64 v[32:33], 12, v[30:31]
	v_lshl_add_u64 v[32:33], v[26:27], 0, v[32:33]
	global_load_dword v184, v[32:33], off
	v_add_u32_e32 v32, 2, v30
	v_ashrrev_i32_e32 v33, 31, v32
	v_lshlrev_b64 v[32:33], 12, v[32:33]
	v_lshl_add_u64 v[32:33], v[26:27], 0, v[32:33]
	s_add_i32 s9, s9, 32
	s_cmp_lg_u32 s9, 64
	global_load_dword v185, v[32:33], off
	v_add_u32_e32 v32, 4, v30
	v_ashrrev_i32_e32 v33, 31, v32
	v_lshlrev_b64 v[32:33], 12, v[32:33]
	v_lshl_add_u64 v[32:33], v[26:27], 0, v[32:33]
	global_load_dword v186, v[32:33], off
	v_add_u32_e32 v32, 6, v30
	v_ashrrev_i32_e32 v33, 31, v32
	v_lshlrev_b64 v[32:33], 12, v[32:33]
	v_lshl_add_u64 v[32:33], v[26:27], 0, v[32:33]
	global_load_dword v187, v[32:33], off
	v_add_u32_e32 v32, 8, v30
	v_ashrrev_i32_e32 v33, 31, v32
	v_lshlrev_b64 v[32:33], 12, v[32:33]
	v_lshl_add_u64 v[32:33], v[26:27], 0, v[32:33]
	global_load_dword v188, v[32:33], off
	v_add_u32_e32 v32, 10, v30
	v_ashrrev_i32_e32 v33, 31, v32
	v_lshlrev_b64 v[32:33], 12, v[32:33]
	v_lshl_add_u64 v[32:33], v[26:27], 0, v[32:33]
	global_load_dword v189, v[32:33], off
	v_add_u32_e32 v32, 12, v30
	v_ashrrev_i32_e32 v33, 31, v32
	v_lshlrev_b64 v[32:33], 12, v[32:33]
	v_lshl_add_u64 v[32:33], v[26:27], 0, v[32:33]
	global_load_dword v190, v[32:33], off
	v_add_u32_e32 v32, 14, v30
	v_ashrrev_i32_e32 v33, 31, v32
	v_lshlrev_b64 v[32:33], 12, v[32:33]
	v_lshl_add_u64 v[32:33], v[26:27], 0, v[32:33]
	global_load_dword v191, v[32:33], off
	v_add_u32_e32 v32, 16, v30
	v_ashrrev_i32_e32 v33, 31, v32
	v_lshlrev_b64 v[32:33], 12, v[32:33]
	v_lshl_add_u64 v[32:33], v[26:27], 0, v[32:33]
	global_load_dword v192, v[32:33], off
	v_add_u32_e32 v32, 18, v30
	v_ashrrev_i32_e32 v33, 31, v32
	v_lshlrev_b64 v[32:33], 12, v[32:33]
	v_lshl_add_u64 v[32:33], v[26:27], 0, v[32:33]
	global_load_dword v193, v[32:33], off
	v_add_u32_e32 v32, 20, v30
	v_ashrrev_i32_e32 v33, 31, v32
	v_lshlrev_b64 v[32:33], 12, v[32:33]
	v_lshl_add_u64 v[32:33], v[26:27], 0, v[32:33]
	global_load_dword v194, v[32:33], off
	v_add_u32_e32 v32, 22, v30
	v_ashrrev_i32_e32 v33, 31, v32
	v_lshlrev_b64 v[32:33], 12, v[32:33]
	v_lshl_add_u64 v[32:33], v[26:27], 0, v[32:33]
	global_load_dword v195, v[32:33], off
	v_add_u32_e32 v32, 24, v30
	v_ashrrev_i32_e32 v33, 31, v32
	v_lshlrev_b64 v[32:33], 12, v[32:33]
	v_lshl_add_u64 v[32:33], v[26:27], 0, v[32:33]
	global_load_dword v196, v[32:33], off
	v_add_u32_e32 v32, 26, v30
	v_ashrrev_i32_e32 v33, 31, v32
	v_lshlrev_b64 v[32:33], 12, v[32:33]
	v_lshl_add_u64 v[32:33], v[26:27], 0, v[32:33]
	global_load_dword v197, v[32:33], off
	v_add_u32_e32 v32, 28, v30
	v_ashrrev_i32_e32 v33, 31, v32
	v_lshlrev_b64 v[32:33], 12, v[32:33]
	v_lshl_add_u64 v[32:33], v[26:27], 0, v[32:33]
	v_add_u32_e32 v30, 30, v30
	v_ashrrev_i32_e32 v31, 31, v30
	v_lshlrev_b64 v[30:31], 12, v[30:31]
	v_lshl_add_u64 v[30:31], v[26:27], 0, v[30:31]
	global_load_dword v198, v[32:33], off
	global_load_dword v199, v[30:31], off
	s_waitcnt vmcnt(0)
	ds_write_b32 v28, v184
	ds_write_b32 v28, v185 offset:264
	ds_write_b32 v28, v186 offset:528
	ds_write_b32 v28, v187 offset:792
	ds_write_b32 v28, v188 offset:1056
	ds_write_b32 v28, v189 offset:1320
	ds_write_b32 v28, v190 offset:1584
	ds_write_b32 v28, v191 offset:1848
	ds_write_b32 v28, v192 offset:2112
	ds_write_b32 v28, v193 offset:2376
	ds_write_b32 v28, v194 offset:2640
	ds_write_b32 v28, v195 offset:2904
	ds_write_b32 v28, v196 offset:3168
	ds_write_b32 v28, v197 offset:3432
	ds_write_b32 v28, v198 offset:3696
	ds_write_b32 v28, v199 offset:3960
	v_add_u32_e32 v28, 0x1080, v28
	s_cbranch_scc1 .LBB0_159
	s_waitcnt lgkmcnt(0)
	ds_read2_b32 v[26:27], v3 offset1:33
	v_or_b32_e32 v30, s8, v1
	s_waitcnt lgkmcnt(0)
	v_cvt_pk_bf16_f32 v26, v26, v27
	ds_read2_b32 v[28:29], v3 offset0:66 offset1:99
	s_ashr_i32 s23, s22, 31
	v_ashrrev_i32_e32 v31, 31, v30
	s_waitcnt lgkmcnt(0)
	v_cvt_pk_bf16_f32 v27, v28, v29
	ds_read2_b32 v[28:29], v3 offset0:132 offset1:165
	v_lshl_add_u64 v[38:39], s[22:23], 1, v[16:17]
	v_lshlrev_b64 v[30:31], 11, v[30:31]
	s_waitcnt lgkmcnt(0)
	v_cvt_pk_bf16_f32 v28, v28, v29
	ds_read2_b32 v[32:33], v3 offset0:198 offset1:231
	v_lshl_add_u64 v[30:31], v[38:39], 0, v[30:31]
	s_waitcnt lgkmcnt(0)
	v_cvt_pk_bf16_f32 v29, v32, v33
	flat_store_dwordx4 v[30:31], v[26:29] sc1
	v_or_b32_e32 v32, s8, v9
	ds_read2_b32 v[26:27], v3 offset0:8 offset1:41
	v_ashrrev_i32_e32 v33, 31, v32
	s_waitcnt lgkmcnt(0)
	v_cvt_pk_bf16_f32 v26, v26, v27
	ds_read2_b32 v[28:29], v3 offset0:74 offset1:107
	v_lshlrev_b64 v[32:33], 11, v[32:33]
	s_waitcnt lgkmcnt(0)
	v_cvt_pk_bf16_f32 v27, v28, v29
	ds_read2_b32 v[28:29], v3 offset0:140 offset1:173
	v_lshl_add_u64 v[32:33], v[38:39], 0, v[32:33]
	s_waitcnt lgkmcnt(0)
	v_cvt_pk_bf16_f32 v28, v28, v29
	ds_read2_b32 v[30:31], v3 offset0:206 offset1:239
	s_waitcnt lgkmcnt(0)
	v_cvt_pk_bf16_f32 v29, v30, v31
	flat_store_dwordx4 v[32:33], v[26:29] sc1
	v_or_b32_e32 v32, s8, v34
	ds_read2_b32 v[26:27], v3 offset0:16 offset1:49
	v_ashrrev_i32_e32 v33, 31, v32
	s_waitcnt lgkmcnt(0)
	v_cvt_pk_bf16_f32 v26, v26, v27
	ds_read2_b32 v[28:29], v3 offset0:82 offset1:115
	v_lshlrev_b64 v[32:33], 11, v[32:33]
	s_waitcnt lgkmcnt(0)
	v_cvt_pk_bf16_f32 v27, v28, v29
	ds_read2_b32 v[28:29], v3 offset0:148 offset1:181
	v_lshl_add_u64 v[32:33], v[38:39], 0, v[32:33]
	s_waitcnt lgkmcnt(0)
	v_cvt_pk_bf16_f32 v28, v28, v29
	ds_read2_b32 v[30:31], v3 offset0:214 offset1:247
	s_waitcnt lgkmcnt(0)
	v_cvt_pk_bf16_f32 v29, v30, v31
	flat_store_dwordx4 v[32:33], v[26:29] sc1
	ds_read2_b32 v[26:27], v3 offset0:24 offset1:57
	v_or_b32_e32 v32, s8, v35
	s_waitcnt lgkmcnt(0)
	v_cvt_pk_bf16_f32 v26, v26, v27
	ds_read2_b32 v[28:29], v3 offset0:90 offset1:123
	s_waitcnt lgkmcnt(0)
	v_cvt_pk_bf16_f32 v27, v28, v29
	ds_read2_b32 v[28:29], v3 offset0:156 offset1:189
	v_ashrrev_i32_e32 v33, 31, v32
	s_waitcnt lgkmcnt(0)
	v_cvt_pk_bf16_f32 v28, v28, v29
	ds_read2_b32 v[30:31], v3 offset0:222 offset1:255
	v_lshlrev_b64 v[32:33], 11, v[32:33]
	s_waitcnt lgkmcnt(0)
	v_cvt_pk_bf16_f32 v29, v30, v31
	v_lshl_add_u64 v[30:31], v[38:39], 0, v[32:33]
	flat_store_dwordx4 v[30:31], v[26:29] sc1
	s_waitcnt lgkmcnt(0)
	s_mov_b64 s[22:23], -1
	s_mov_b32 s10, s33

.LBB0_206:
	s_lshl_b32 s41, s62, 6
	s_and_b32 s40, s40, 0x60
	s_and_b32 s41, s41, 0xffffff00
	s_waitcnt lgkmcnt(0)
	s_lshl_b64 s[8:9], s[42:43], 1
	s_or_b32 s40, s41, s40
	ds_read2_b32 v[26:27], v3 offset1:33
	s_add_u32 s8, s60, s8
	v_or_b32_e32 v30, s40, v1
	s_waitcnt lgkmcnt(0)
	v_cvt_pk_bf16_f32 v26, v26, v27
	ds_read2_b32 v[28:29], v3 offset0:66 offset1:99
	v_lshlrev_b32_e32 v4, 1, v8
	s_addc_u32 s9, s61, s9
	v_ashrrev_i32_e32 v31, 31, v30
	s_waitcnt lgkmcnt(0)
	v_cvt_pk_bf16_f32 v27, v28, v29
	ds_read2_b32 v[28:29], v3 offset0:132 offset1:165
	v_lshl_add_u64 v[38:39], s[8:9], 0, v[4:5]
	v_lshlrev_b64 v[30:31], 11, v[30:31]
	s_waitcnt lgkmcnt(0)
	v_cvt_pk_bf16_f32 v28, v28, v29
	ds_read2_b32 v[32:33], v3 offset0:198 offset1:231
	v_lshl_add_u64 v[30:31], v[38:39], 0, v[30:31]
	s_waitcnt lgkmcnt(0)
	v_cvt_pk_bf16_f32 v29, v32, v33
	flat_store_dwordx4 v[30:31], v[26:29] sc1
	v_or_b32_e32 v32, s40, v9
	ds_read2_b32 v[26:27], v3 offset0:8 offset1:41
	v_ashrrev_i32_e32 v33, 31, v32
	s_waitcnt lgkmcnt(0)
	v_cvt_pk_bf16_f32 v26, v26, v27
	ds_read2_b32 v[28:29], v3 offset0:74 offset1:107
	v_lshlrev_b64 v[32:33], 11, v[32:33]
	s_waitcnt lgkmcnt(0)
	v_cvt_pk_bf16_f32 v27, v28, v29
	ds_read2_b32 v[28:29], v3 offset0:140 offset1:173
	v_lshl_add_u64 v[32:33], v[38:39], 0, v[32:33]
	s_waitcnt lgkmcnt(0)
	v_cvt_pk_bf16_f32 v28, v28, v29
	ds_read2_b32 v[30:31], v3 offset0:206 offset1:239
	s_waitcnt lgkmcnt(0)
	v_cvt_pk_bf16_f32 v29, v30, v31
	flat_store_dwordx4 v[32:33], v[26:29] sc1
	v_or_b32_e32 v32, s40, v34
	ds_read2_b32 v[26:27], v3 offset0:16 offset1:49
	v_ashrrev_i32_e32 v33, 31, v32
	s_waitcnt lgkmcnt(0)
	v_cvt_pk_bf16_f32 v26, v26, v27
	ds_read2_b32 v[28:29], v3 offset0:82 offset1:115
	v_lshlrev_b64 v[32:33], 11, v[32:33]
	s_waitcnt lgkmcnt(0)
	v_cvt_pk_bf16_f32 v27, v28, v29
	ds_read2_b32 v[28:29], v3 offset0:148 offset1:181
	v_lshl_add_u64 v[32:33], v[38:39], 0, v[32:33]
	s_waitcnt lgkmcnt(0)
	v_cvt_pk_bf16_f32 v28, v28, v29
	ds_read2_b32 v[30:31], v3 offset0:214 offset1:247
	s_waitcnt lgkmcnt(0)
	v_cvt_pk_bf16_f32 v29, v30, v31
	flat_store_dwordx4 v[32:33], v[26:29] sc1
	ds_read2_b32 v[26:27], v3 offset0:24 offset1:57
	v_or_b32_e32 v32, s40, v35
	s_waitcnt lgkmcnt(0)
	v_cvt_pk_bf16_f32 v26, v26, v27
	ds_read2_b32 v[28:29], v3 offset0:90 offset1:123
	s_waitcnt lgkmcnt(0)
	v_cvt_pk_bf16_f32 v27, v28, v29
	ds_read2_b32 v[28:29], v3 offset0:156 offset1:189
	v_ashrrev_i32_e32 v33, 31, v32
	s_waitcnt lgkmcnt(0)
	v_cvt_pk_bf16_f32 v28, v28, v29
	ds_read2_b32 v[30:31], v3 offset0:222 offset1:255
	v_lshlrev_b64 v[32:33], 11, v[32:33]
	s_waitcnt lgkmcnt(0)
	v_cvt_pk_bf16_f32 v29, v30, v31
	v_lshl_add_u64 v[30:31], v[38:39], 0, v[32:33]
	flat_store_dwordx4 v[30:31], v[26:29] sc1
	s_waitcnt lgkmcnt(0)
	s_mov_b32 s42, s33

.LBB0_246:
	s_lshl_b32 s26, s33, 6
	s_and_b32 s27, s36, 0x60
	s_and_b32 s26, s26, 0xffffff00
	s_or_b32 s26, s27, s26
	s_waitcnt lgkmcnt(0)
	s_lshl_b64 s[8:9], s[38:39], 1
	s_bitset1_b32 s26, 7
	ds_read2_b32 v[26:27], v3 offset1:33
	s_add_u32 s8, s60, s8
	v_or_b32_e32 v30, s26, v1
	s_waitcnt lgkmcnt(0)
	v_cvt_pk_bf16_f32 v26, v26, v27
	ds_read2_b32 v[28:29], v3 offset0:66 offset1:99
	v_lshlrev_b32_e32 v4, 1, v8
	s_addc_u32 s9, s61, s9
	v_ashrrev_i32_e32 v31, 31, v30
	s_waitcnt lgkmcnt(0)
	v_cvt_pk_bf16_f32 v27, v28, v29
	ds_read2_b32 v[28:29], v3 offset0:132 offset1:165
	v_lshl_add_u64 v[38:39], s[8:9], 0, v[4:5]
	v_lshlrev_b64 v[30:31], 11, v[30:31]
	s_waitcnt lgkmcnt(0)
	v_cvt_pk_bf16_f32 v28, v28, v29
	ds_read2_b32 v[32:33], v3 offset0:198 offset1:231
	v_lshl_add_u64 v[30:31], v[38:39], 0, v[30:31]
	s_waitcnt lgkmcnt(0)
	v_cvt_pk_bf16_f32 v29, v32, v33
	flat_store_dwordx4 v[30:31], v[26:29] sc1
	v_or_b32_e32 v32, s26, v9
	ds_read2_b32 v[26:27], v3 offset0:8 offset1:41
	v_ashrrev_i32_e32 v33, 31, v32
	s_waitcnt lgkmcnt(0)
	v_cvt_pk_bf16_f32 v26, v26, v27
	ds_read2_b32 v[28:29], v3 offset0:74 offset1:107
	v_lshlrev_b64 v[32:33], 11, v[32:33]
	s_waitcnt lgkmcnt(0)
	v_cvt_pk_bf16_f32 v27, v28, v29
	ds_read2_b32 v[28:29], v3 offset0:140 offset1:173
	v_lshl_add_u64 v[32:33], v[38:39], 0, v[32:33]
	s_waitcnt lgkmcnt(0)
	v_cvt_pk_bf16_f32 v28, v28, v29
	ds_read2_b32 v[30:31], v3 offset0:206 offset1:239
	s_waitcnt lgkmcnt(0)
	v_cvt_pk_bf16_f32 v29, v30, v31
	flat_store_dwordx4 v[32:33], v[26:29] sc1
	v_or_b32_e32 v32, s26, v34
	ds_read2_b32 v[26:27], v3 offset0:16 offset1:49
	v_ashrrev_i32_e32 v33, 31, v32
	s_waitcnt lgkmcnt(0)
	v_cvt_pk_bf16_f32 v26, v26, v27
	ds_read2_b32 v[28:29], v3 offset0:82 offset1:115
	v_lshlrev_b64 v[32:33], 11, v[32:33]
	s_waitcnt lgkmcnt(0)
	v_cvt_pk_bf16_f32 v27, v28, v29
	ds_read2_b32 v[28:29], v3 offset0:148 offset1:181
	v_lshl_add_u64 v[32:33], v[38:39], 0, v[32:33]
	s_waitcnt lgkmcnt(0)
	v_cvt_pk_bf16_f32 v28, v28, v29
	ds_read2_b32 v[30:31], v3 offset0:214 offset1:247
	s_waitcnt lgkmcnt(0)
	v_cvt_pk_bf16_f32 v29, v30, v31
	flat_store_dwordx4 v[32:33], v[26:29] sc1
	ds_read2_b32 v[26:27], v3 offset0:24 offset1:57
	v_or_b32_e32 v32, s26, v35
	s_waitcnt lgkmcnt(0)
	v_cvt_pk_bf16_f32 v26, v26, v27
	ds_read2_b32 v[28:29], v3 offset0:90 offset1:123
	s_waitcnt lgkmcnt(0)
	v_cvt_pk_bf16_f32 v27, v28, v29
	ds_read2_b32 v[28:29], v3 offset0:156 offset1:189
	v_ashrrev_i32_e32 v33, 31, v32
	s_waitcnt lgkmcnt(0)
	v_cvt_pk_bf16_f32 v28, v28, v29
	ds_read2_b32 v[30:31], v3 offset0:222 offset1:255
	v_lshlrev_b64 v[32:33], 11, v[32:33]
	s_waitcnt lgkmcnt(0)
	v_cvt_pk_bf16_f32 v29, v30, v31
	v_lshl_add_u64 v[30:31], v[38:39], 0, v[32:33]
	flat_store_dwordx4 v[30:31], v[26:29] sc1
	s_waitcnt lgkmcnt(0)
	s_mov_b64 s[8:9], -1
	s_mov_b32 s33, s42

.LBB0_252:
	v_add_u32_e32 v30, s9, v4
	v_ashrrev_i32_e32 v31, 31, v30
	v_lshlrev_b64 v[32:33], 12, v[30:31]
	v_lshl_add_u64 v[32:33], v[26:27], 0, v[32:33]
	global_load_dword v184, v[32:33], off
	v_add_u32_e32 v32, 2, v30
	v_ashrrev_i32_e32 v33, 31, v32
	v_lshlrev_b64 v[32:33], 12, v[32:33]
	v_lshl_add_u64 v[32:33], v[26:27], 0, v[32:33]
	s_add_i32 s9, s9, 32
	s_cmp_lg_u32 s9, 64
	global_load_dword v185, v[32:33], off
	v_add_u32_e32 v32, 4, v30
	v_ashrrev_i32_e32 v33, 31, v32
	v_lshlrev_b64 v[32:33], 12, v[32:33]
	v_lshl_add_u64 v[32:33], v[26:27], 0, v[32:33]
	global_load_dword v186, v[32:33], off
	v_add_u32_e32 v32, 6, v30
	v_ashrrev_i32_e32 v33, 31, v32
	v_lshlrev_b64 v[32:33], 12, v[32:33]
	v_lshl_add_u64 v[32:33], v[26:27], 0, v[32:33]
	global_load_dword v187, v[32:33], off
	v_add_u32_e32 v32, 8, v30
	v_ashrrev_i32_e32 v33, 31, v32
	v_lshlrev_b64 v[32:33], 12, v[32:33]
	v_lshl_add_u64 v[32:33], v[26:27], 0, v[32:33]
	global_load_dword v188, v[32:33], off
	v_add_u32_e32 v32, 10, v30
	v_ashrrev_i32_e32 v33, 31, v32
	v_lshlrev_b64 v[32:33], 12, v[32:33]
	v_lshl_add_u64 v[32:33], v[26:27], 0, v[32:33]
	global_load_dword v189, v[32:33], off
	v_add_u32_e32 v32, 12, v30
	v_ashrrev_i32_e32 v33, 31, v32
	v_lshlrev_b64 v[32:33], 12, v[32:33]
	v_lshl_add_u64 v[32:33], v[26:27], 0, v[32:33]
	global_load_dword v190, v[32:33], off
	v_add_u32_e32 v32, 14, v30
	v_ashrrev_i32_e32 v33, 31, v32
	v_lshlrev_b64 v[32:33], 12, v[32:33]
	v_lshl_add_u64 v[32:33], v[26:27], 0, v[32:33]
	global_load_dword v191, v[32:33], off
	v_add_u32_e32 v32, 16, v30
	v_ashrrev_i32_e32 v33, 31, v32
	v_lshlrev_b64 v[32:33], 12, v[32:33]
	v_lshl_add_u64 v[32:33], v[26:27], 0, v[32:33]
	global_load_dword v192, v[32:33], off
	v_add_u32_e32 v32, 18, v30
	v_ashrrev_i32_e32 v33, 31, v32
	v_lshlrev_b64 v[32:33], 12, v[32:33]
	v_lshl_add_u64 v[32:33], v[26:27], 0, v[32:33]
	global_load_dword v193, v[32:33], off
	v_add_u32_e32 v32, 20, v30
	v_ashrrev_i32_e32 v33, 31, v32
	v_lshlrev_b64 v[32:33], 12, v[32:33]
	v_lshl_add_u64 v[32:33], v[26:27], 0, v[32:33]
	global_load_dword v194, v[32:33], off
	v_add_u32_e32 v32, 22, v30
	v_ashrrev_i32_e32 v33, 31, v32
	v_lshlrev_b64 v[32:33], 12, v[32:33]
	v_lshl_add_u64 v[32:33], v[26:27], 0, v[32:33]
	global_load_dword v195, v[32:33], off
	v_add_u32_e32 v32, 24, v30
	v_ashrrev_i32_e32 v33, 31, v32
	v_lshlrev_b64 v[32:33], 12, v[32:33]
	v_lshl_add_u64 v[32:33], v[26:27], 0, v[32:33]
	global_load_dword v196, v[32:33], off
	v_add_u32_e32 v32, 26, v30
	v_ashrrev_i32_e32 v33, 31, v32
	v_lshlrev_b64 v[32:33], 12, v[32:33]
	v_lshl_add_u64 v[32:33], v[26:27], 0, v[32:33]
	global_load_dword v197, v[32:33], off
	v_add_u32_e32 v32, 28, v30
	v_ashrrev_i32_e32 v33, 31, v32
	v_lshlrev_b64 v[32:33], 12, v[32:33]
	v_lshl_add_u64 v[32:33], v[26:27], 0, v[32:33]
	v_add_u32_e32 v30, 30, v30
	v_ashrrev_i32_e32 v31, 31, v30
	v_lshlrev_b64 v[30:31], 12, v[30:31]
	v_lshl_add_u64 v[30:31], v[26:27], 0, v[30:31]
	global_load_dword v198, v[32:33], off
	global_load_dword v199, v[30:31], off
	s_waitcnt vmcnt(0)
	ds_write_b32 v28, v184
	ds_write_b32 v28, v185 offset:264
	ds_write_b32 v28, v186 offset:528
	ds_write_b32 v28, v187 offset:792
	ds_write_b32 v28, v188 offset:1056
	ds_write_b32 v28, v189 offset:1320
	ds_write_b32 v28, v190 offset:1584
	ds_write_b32 v28, v191 offset:1848
	ds_write_b32 v28, v192 offset:2112
	ds_write_b32 v28, v193 offset:2376
	ds_write_b32 v28, v194 offset:2640
	ds_write_b32 v28, v195 offset:2904
	ds_write_b32 v28, v196 offset:3168
	ds_write_b32 v28, v197 offset:3432
	ds_write_b32 v28, v198 offset:3696
	ds_write_b32 v28, v199 offset:3960
	v_add_u32_e32 v28, 0x1080, v28
	s_cbranch_scc1 .LBB0_252
	s_ashr_i32 s25, s24, 31
	s_lshl_b64 s[24:25], s[24:25], 1
	s_add_u32 s24, s60, s24
	s_waitcnt lgkmcnt(0)
	v_lshlrev_b32_e32 v4, 1, v8
	s_addc_u32 s25, s61, s25
	ds_read2_b32 v[26:27], v3 offset1:33
	v_lshl_add_u64 v[32:33], s[24:25], 0, v[4:5]
	s_waitcnt lgkmcnt(0)
	v_cvt_pk_bf16_f32 v26, v26, v27
	ds_read2_b32 v[28:29], v3 offset0:66 offset1:99
	v_or_b32_e32 v37, s8, v1
	v_lshl_add_u64 v[32:33], v[32:33], 0, s[20:21]
	s_waitcnt lgkmcnt(0)
	v_cvt_pk_bf16_f32 v27, v28, v29
	ds_read2_b32 v[28:29], v3 offset0:132 offset1:165
	v_mad_i64_i32 v[38:39], s[24:25], v37, s46, v[32:33]
	s_waitcnt lgkmcnt(0)
	v_cvt_pk_bf16_f32 v28, v28, v29
	ds_read2_b32 v[30:31], v3 offset0:198 offset1:231
	s_waitcnt lgkmcnt(0)
	v_cvt_pk_bf16_f32 v29, v30, v31
	flat_store_dwordx4 v[38:39], v[26:29] sc1
	ds_read2_b32 v[26:27], v3 offset0:8 offset1:41
	v_or_b32_e32 v4, s8, v9
	s_waitcnt lgkmcnt(0)
	v_cvt_pk_bf16_f32 v26, v26, v27
	ds_read2_b32 v[28:29], v3 offset0:74 offset1:107
	s_waitcnt lgkmcnt(0)
	v_cvt_pk_bf16_f32 v27, v28, v29
	ds_read2_b32 v[28:29], v3 offset0:140 offset1:173
	v_mad_i64_i32 v[38:39], s[24:25], v4, s46, v[32:33]
	s_waitcnt lgkmcnt(0)
	v_cvt_pk_bf16_f32 v28, v28, v29
	ds_read2_b32 v[30:31], v3 offset0:206 offset1:239
	s_waitcnt lgkmcnt(0)
	v_cvt_pk_bf16_f32 v29, v30, v31
	flat_store_dwordx4 v[38:39], v[26:29] sc1
	ds_read2_b32 v[26:27], v3 offset0:16 offset1:49
	v_or_b32_e32 v4, s8, v34
	s_waitcnt lgkmcnt(0)
	v_cvt_pk_bf16_f32 v26, v26, v27
	ds_read2_b32 v[28:29], v3 offset0:82 offset1:115
	s_waitcnt lgkmcnt(0)
	v_cvt_pk_bf16_f32 v27, v28, v29
	ds_read2_b32 v[28:29], v3 offset0:148 offset1:181
	v_mad_i64_i32 v[38:39], s[24:25], v4, s46, v[32:33]
	s_waitcnt lgkmcnt(0)
	v_cvt_pk_bf16_f32 v28, v28, v29
	ds_read2_b32 v[30:31], v3 offset0:214 offset1:247
	s_waitcnt lgkmcnt(0)
	v_cvt_pk_bf16_f32 v29, v30, v31
	flat_store_dwordx4 v[38:39], v[26:29] sc1
	ds_read2_b32 v[26:27], v3 offset0:24 offset1:57
	v_or_b32_e32 v4, s8, v35
	s_waitcnt lgkmcnt(0)
	v_cvt_pk_bf16_f32 v26, v26, v27
	ds_read2_b32 v[28:29], v3 offset0:90 offset1:123
	s_waitcnt lgkmcnt(0)
	v_cvt_pk_bf16_f32 v27, v28, v29
	ds_read2_b32 v[28:29], v3 offset0:156 offset1:189
	s_waitcnt lgkmcnt(0)
	v_cvt_pk_bf16_f32 v28, v28, v29
	ds_read2_b32 v[30:31], v3 offset0:222 offset1:255
	s_waitcnt lgkmcnt(0)
	v_cvt_pk_bf16_f32 v29, v30, v31
	v_mad_i64_i32 v[30:31], s[8:9], v4, s46, v[32:33]
	flat_store_dwordx4 v[30:31], v[26:29] sc1
	s_waitcnt lgkmcnt(0)
	s_mov_b64 s[34:35], -1

.LBB0_263:
	v_add_u32_e32 v30, s10, v4
	v_ashrrev_i32_e32 v31, 31, v30
	v_mad_i64_i32 v[32:33], s[28:29], v30, s48, v[26:27]
	flat_load_dword v29, v[32:33]
	v_lshl_add_u64 v[32:33], v[30:31], 2, s[26:27]
	flat_load_dword v31, v[32:33]
	v_add_u32_e32 v32, 2, v30
	v_ashrrev_i32_e32 v33, 31, v32
	v_mad_i64_i32 v[38:39], s[28:29], v32, s48, v[26:27]
	v_lshl_add_u64 v[32:33], v[32:33], 2, s[26:27]
	s_add_i32 s10, s10, 32
	s_cmp_lg_u32 s10, 64
	s_waitcnt vmcnt(0) lgkmcnt(0)
	v_mul_f32_e32 v29, v29, v31
	ds_write_b32 v28, v29
	flat_load_dword v29, v[38:39]
	flat_load_dword v31, v[32:33]
	v_add_u32_e32 v32, 4, v30
	v_ashrrev_i32_e32 v33, 31, v32
	v_mad_i64_i32 v[38:39], s[28:29], v32, s48, v[26:27]
	v_lshl_add_u64 v[32:33], v[32:33], 2, s[26:27]
	s_waitcnt vmcnt(0) lgkmcnt(0)
	v_mul_f32_e32 v29, v29, v31
	ds_write_b32 v28, v29 offset:264
	flat_load_dword v29, v[38:39]
	flat_load_dword v31, v[32:33]
	v_add_u32_e32 v32, 6, v30
	v_ashrrev_i32_e32 v33, 31, v32
	v_mad_i64_i32 v[38:39], s[28:29], v32, s48, v[26:27]
	v_lshl_add_u64 v[32:33], v[32:33], 2, s[26:27]
	s_waitcnt vmcnt(0) lgkmcnt(0)
	v_mul_f32_e32 v29, v29, v31
	ds_write_b32 v28, v29 offset:528
	flat_load_dword v29, v[38:39]
	flat_load_dword v31, v[32:33]
	v_add_u32_e32 v32, 8, v30
	v_ashrrev_i32_e32 v33, 31, v32
	v_mad_i64_i32 v[38:39], s[28:29], v32, s48, v[26:27]
	v_lshl_add_u64 v[32:33], v[32:33], 2, s[26:27]
	s_waitcnt vmcnt(0) lgkmcnt(0)
	v_mul_f32_e32 v29, v29, v31
	ds_write_b32 v28, v29 offset:792
	flat_load_dword v29, v[38:39]
	flat_load_dword v31, v[32:33]
	v_add_u32_e32 v32, 10, v30
	v_ashrrev_i32_e32 v33, 31, v32
	v_mad_i64_i32 v[38:39], s[28:29], v32, s48, v[26:27]
	v_lshl_add_u64 v[32:33], v[32:33], 2, s[26:27]
	s_waitcnt vmcnt(0) lgkmcnt(0)
	v_mul_f32_e32 v29, v29, v31
	ds_write_b32 v28, v29 offset:1056
	flat_load_dword v29, v[38:39]
	flat_load_dword v31, v[32:33]
	v_add_u32_e32 v32, 12, v30
	v_ashrrev_i32_e32 v33, 31, v32
	v_mad_i64_i32 v[38:39], s[28:29], v32, s48, v[26:27]
	v_lshl_add_u64 v[32:33], v[32:33], 2, s[26:27]
	s_waitcnt vmcnt(0) lgkmcnt(0)
	v_mul_f32_e32 v29, v29, v31
	ds_write_b32 v28, v29 offset:1320
	flat_load_dword v29, v[38:39]
	flat_load_dword v31, v[32:33]
	v_add_u32_e32 v32, 14, v30
	v_ashrrev_i32_e32 v33, 31, v32
	v_mad_i64_i32 v[38:39], s[28:29], v32, s48, v[26:27]
	v_lshl_add_u64 v[32:33], v[32:33], 2, s[26:27]
	s_waitcnt vmcnt(0) lgkmcnt(0)
	v_mul_f32_e32 v29, v29, v31
	ds_write_b32 v28, v29 offset:1584
	flat_load_dword v29, v[38:39]
	flat_load_dword v31, v[32:33]
	v_add_u32_e32 v32, 16, v30
	v_ashrrev_i32_e32 v33, 31, v32
	v_mad_i64_i32 v[38:39], s[28:29], v32, s48, v[26:27]
	v_lshl_add_u64 v[32:33], v[32:33], 2, s[26:27]
	s_waitcnt vmcnt(0) lgkmcnt(0)
	v_mul_f32_e32 v29, v29, v31
	ds_write_b32 v28, v29 offset:1848
	flat_load_dword v29, v[38:39]
	flat_load_dword v31, v[32:33]
	v_add_u32_e32 v32, 18, v30
	v_ashrrev_i32_e32 v33, 31, v32
	v_mad_i64_i32 v[38:39], s[28:29], v32, s48, v[26:27]
	v_lshl_add_u64 v[32:33], v[32:33], 2, s[26:27]
	s_waitcnt vmcnt(0) lgkmcnt(0)
	v_mul_f32_e32 v29, v29, v31
	ds_write_b32 v28, v29 offset:2112
	flat_load_dword v29, v[38:39]
	flat_load_dword v31, v[32:33]
	v_add_u32_e32 v32, 20, v30
	v_ashrrev_i32_e32 v33, 31, v32
	v_mad_i64_i32 v[38:39], s[28:29], v32, s48, v[26:27]
	v_lshl_add_u64 v[32:33], v[32:33], 2, s[26:27]
	s_waitcnt vmcnt(0) lgkmcnt(0)
	v_mul_f32_e32 v29, v29, v31
	ds_write_b32 v28, v29 offset:2376
	flat_load_dword v29, v[38:39]
	flat_load_dword v31, v[32:33]
	v_add_u32_e32 v32, 22, v30
	v_ashrrev_i32_e32 v33, 31, v32
	v_mad_i64_i32 v[38:39], s[28:29], v32, s48, v[26:27]
	v_lshl_add_u64 v[32:33], v[32:33], 2, s[26:27]
	s_waitcnt vmcnt(0) lgkmcnt(0)
	v_mul_f32_e32 v29, v29, v31
	ds_write_b32 v28, v29 offset:2640
	flat_load_dword v29, v[38:39]
	flat_load_dword v31, v[32:33]
	v_add_u32_e32 v32, 24, v30
	v_ashrrev_i32_e32 v33, 31, v32
	v_mad_i64_i32 v[38:39], s[28:29], v32, s48, v[26:27]
	v_lshl_add_u64 v[32:33], v[32:33], 2, s[26:27]
	s_waitcnt vmcnt(0) lgkmcnt(0)
	v_mul_f32_e32 v29, v29, v31
	ds_write_b32 v28, v29 offset:2904
	flat_load_dword v29, v[38:39]
	flat_load_dword v31, v[32:33]
	v_add_u32_e32 v32, 26, v30
	v_ashrrev_i32_e32 v33, 31, v32
	v_mad_i64_i32 v[38:39], s[28:29], v32, s48, v[26:27]
	v_lshl_add_u64 v[32:33], v[32:33], 2, s[26:27]
	s_waitcnt vmcnt(0) lgkmcnt(0)
	v_mul_f32_e32 v29, v29, v31
	ds_write_b32 v28, v29 offset:3168
	flat_load_dword v29, v[38:39]
	flat_load_dword v31, v[32:33]
	v_add_u32_e32 v32, 28, v30
	v_ashrrev_i32_e32 v33, 31, v32
	v_mad_i64_i32 v[38:39], s[28:29], v32, s48, v[26:27]
	v_lshl_add_u64 v[32:33], v[32:33], 2, s[26:27]
	v_add_u32_e32 v30, 30, v30
	s_waitcnt vmcnt(0) lgkmcnt(0)
	v_mul_f32_e32 v29, v29, v31
	ds_write_b32 v28, v29 offset:3432
	flat_load_dword v29, v[38:39]
	flat_load_dword v37, v[32:33]
	v_ashrrev_i32_e32 v31, 31, v30
	v_mad_i64_i32 v[32:33], s[28:29], v30, s48, v[26:27]
	v_lshl_add_u64 v[30:31], v[30:31], 2, s[26:27]
	s_waitcnt vmcnt(0) lgkmcnt(0)
	v_mul_f32_e32 v29, v29, v37
	ds_write_b32 v28, v29 offset:3696
	flat_load_dword v29, v[32:33]
	flat_load_dword v37, v[30:31]
	s_waitcnt vmcnt(0) lgkmcnt(0)
	v_mul_f32_e32 v29, v29, v37
	ds_write_b32 v28, v29 offset:3960
	v_add_u32_e32 v28, 0x1080, v28
	s_cbranch_scc1 .LBB0_263
	s_waitcnt lgkmcnt(0)
	ds_read2_b32 v[26:27], v3 offset1:33
	v_or_b32_e32 v30, s22, v1
	s_waitcnt lgkmcnt(0)
	v_cvt_pk_bf16_f32 v26, v26, v27
	ds_read2_b32 v[28:29], v3 offset0:66 offset1:99
	s_ashr_i32 s25, s24, 31
	v_ashrrev_i32_e32 v31, 31, v30
	s_waitcnt lgkmcnt(0)
	v_cvt_pk_bf16_f32 v27, v28, v29
	ds_read2_b32 v[28:29], v3 offset0:132 offset1:165
	v_lshl_add_u64 v[38:39], s[24:25], 1, v[18:19]
	v_lshlrev_b64 v[30:31], 11, v[30:31]
	s_waitcnt lgkmcnt(0)
	v_cvt_pk_bf16_f32 v28, v28, v29
	ds_read2_b32 v[32:33], v3 offset0:198 offset1:231
	v_lshl_add_u64 v[30:31], v[38:39], 0, v[30:31]
	s_waitcnt lgkmcnt(0)
	v_cvt_pk_bf16_f32 v29, v32, v33
	flat_store_dwordx4 v[30:31], v[26:29] sc1
	v_or_b32_e32 v32, s22, v9
	ds_read2_b32 v[26:27], v3 offset0:8 offset1:41
	v_ashrrev_i32_e32 v33, 31, v32
	s_waitcnt lgkmcnt(0)
	v_cvt_pk_bf16_f32 v26, v26, v27
	ds_read2_b32 v[28:29], v3 offset0:74 offset1:107
	v_lshlrev_b64 v[32:33], 11, v[32:33]
	s_waitcnt lgkmcnt(0)
	v_cvt_pk_bf16_f32 v27, v28, v29
	ds_read2_b32 v[28:29], v3 offset0:140 offset1:173
	v_lshl_add_u64 v[32:33], v[38:39], 0, v[32:33]
	s_waitcnt lgkmcnt(0)
	v_cvt_pk_bf16_f32 v28, v28, v29
	ds_read2_b32 v[30:31], v3 offset0:206 offset1:239
	s_waitcnt lgkmcnt(0)
	v_cvt_pk_bf16_f32 v29, v30, v31
	flat_store_dwordx4 v[32:33], v[26:29] sc1
	v_or_b32_e32 v32, s22, v34
	ds_read2_b32 v[26:27], v3 offset0:16 offset1:49
	v_ashrrev_i32_e32 v33, 31, v32
	s_waitcnt lgkmcnt(0)
	v_cvt_pk_bf16_f32 v26, v26, v27
	ds_read2_b32 v[28:29], v3 offset0:82 offset1:115
	v_lshlrev_b64 v[32:33], 11, v[32:33]
	s_waitcnt lgkmcnt(0)
	v_cvt_pk_bf16_f32 v27, v28, v29
	ds_read2_b32 v[28:29], v3 offset0:148 offset1:181
	v_lshl_add_u64 v[32:33], v[38:39], 0, v[32:33]
	s_waitcnt lgkmcnt(0)
	v_cvt_pk_bf16_f32 v28, v28, v29
	ds_read2_b32 v[30:31], v3 offset0:214 offset1:247
	s_waitcnt lgkmcnt(0)
	v_cvt_pk_bf16_f32 v29, v30, v31
	flat_store_dwordx4 v[32:33], v[26:29] sc1
	ds_read2_b32 v[26:27], v3 offset0:24 offset1:57
	v_or_b32_e32 v32, s22, v35
	s_waitcnt lgkmcnt(0)
	v_cvt_pk_bf16_f32 v26, v26, v27
	ds_read2_b32 v[28:29], v3 offset0:90 offset1:123
	s_waitcnt lgkmcnt(0)
	v_cvt_pk_bf16_f32 v27, v28, v29
	ds_read2_b32 v[28:29], v3 offset0:156 offset1:189
	v_ashrrev_i32_e32 v33, 31, v32
	s_waitcnt lgkmcnt(0)
	v_cvt_pk_bf16_f32 v28, v28, v29
	ds_read2_b32 v[30:31], v3 offset0:222 offset1:255
	v_lshlrev_b64 v[32:33], 11, v[32:33]
	s_waitcnt lgkmcnt(0)
	v_cvt_pk_bf16_f32 v29, v30, v31
	v_lshl_add_u64 v[30:31], v[38:39], 0, v[32:33]
	flat_store_dwordx4 v[30:31], v[26:29] sc1
	s_waitcnt lgkmcnt(0)
	s_mov_b32 s10, s33
	s_andn2_b64 vcc, exec, s[8:9]
	s_cbranch_vccnz .LBB0_27

.LBB0_278:
	v_add_u32_e32 v29, s23, v4
	v_mad_i64_i32 v[30:31], s[24:25], v29, s49, v[26:27]
	flat_load_dword v32, v[30:31]
	v_add_u32_e32 v30, 2, v29
	v_mad_i64_i32 v[30:31], s[24:25], v30, s49, v[26:27]
	s_add_i32 s23, s23, 32
	s_cmp_lg_u32 s23, 64
	s_waitcnt vmcnt(0) lgkmcnt(0)
	ds_write_b32 v28, v32
	flat_load_dword v32, v[30:31]
	v_add_u32_e32 v30, 4, v29
	v_mad_i64_i32 v[30:31], s[24:25], v30, s49, v[26:27]
	s_waitcnt vmcnt(0) lgkmcnt(0)
	ds_write_b32 v28, v32 offset:264
	flat_load_dword v32, v[30:31]
	v_add_u32_e32 v30, 6, v29
	v_mad_i64_i32 v[30:31], s[24:25], v30, s49, v[26:27]
	s_waitcnt vmcnt(0) lgkmcnt(0)
	ds_write_b32 v28, v32 offset:528
	flat_load_dword v32, v[30:31]
	v_add_u32_e32 v30, 8, v29
	v_mad_i64_i32 v[30:31], s[24:25], v30, s49, v[26:27]
	s_waitcnt vmcnt(0) lgkmcnt(0)
	ds_write_b32 v28, v32 offset:792
	flat_load_dword v32, v[30:31]
	v_add_u32_e32 v30, 10, v29
	v_mad_i64_i32 v[30:31], s[24:25], v30, s49, v[26:27]
	s_waitcnt vmcnt(0) lgkmcnt(0)
	ds_write_b32 v28, v32 offset:1056
	flat_load_dword v32, v[30:31]
	v_add_u32_e32 v30, 12, v29
	v_mad_i64_i32 v[30:31], s[24:25], v30, s49, v[26:27]
	s_waitcnt vmcnt(0) lgkmcnt(0)
	ds_write_b32 v28, v32 offset:1320
	flat_load_dword v32, v[30:31]
	v_add_u32_e32 v30, 14, v29
	v_mad_i64_i32 v[30:31], s[24:25], v30, s49, v[26:27]
	s_waitcnt vmcnt(0) lgkmcnt(0)
	ds_write_b32 v28, v32 offset:1584
	flat_load_dword v32, v[30:31]
	v_add_u32_e32 v30, 16, v29
	v_mad_i64_i32 v[30:31], s[24:25], v30, s49, v[26:27]
	s_waitcnt vmcnt(0) lgkmcnt(0)
	ds_write_b32 v28, v32 offset:1848
	flat_load_dword v32, v[30:31]
	v_add_u32_e32 v30, 18, v29
	v_mad_i64_i32 v[30:31], s[24:25], v30, s49, v[26:27]
	s_waitcnt vmcnt(0) lgkmcnt(0)
	ds_write_b32 v28, v32 offset:2112
	flat_load_dword v32, v[30:31]
	v_add_u32_e32 v30, 20, v29
	v_mad_i64_i32 v[30:31], s[24:25], v30, s49, v[26:27]
	s_waitcnt vmcnt(0) lgkmcnt(0)
	ds_write_b32 v28, v32 offset:2376
	flat_load_dword v32, v[30:31]
	v_add_u32_e32 v30, 22, v29
	v_mad_i64_i32 v[30:31], s[24:25], v30, s49, v[26:27]
	s_waitcnt vmcnt(0) lgkmcnt(0)
	ds_write_b32 v28, v32 offset:2640
	flat_load_dword v32, v[30:31]
	v_add_u32_e32 v30, 24, v29
	v_mad_i64_i32 v[30:31], s[24:25], v30, s49, v[26:27]
	s_waitcnt vmcnt(0) lgkmcnt(0)
	ds_write_b32 v28, v32 offset:2904
	flat_load_dword v32, v[30:31]
	v_add_u32_e32 v30, 26, v29
	v_mad_i64_i32 v[30:31], s[24:25], v30, s49, v[26:27]
	s_waitcnt vmcnt(0) lgkmcnt(0)
	ds_write_b32 v28, v32 offset:3168
	flat_load_dword v32, v[30:31]
	v_add_u32_e32 v30, 28, v29
	v_mad_i64_i32 v[30:31], s[24:25], v30, s49, v[26:27]
	v_add_u32_e32 v29, 30, v29
	s_waitcnt vmcnt(0) lgkmcnt(0)
	ds_write_b32 v28, v32 offset:3432
	flat_load_dword v32, v[30:31]
	v_mad_i64_i32 v[30:31], s[24:25], v29, s49, v[26:27]
	s_waitcnt vmcnt(0) lgkmcnt(0)
	ds_write_b32 v28, v32 offset:3696
	flat_load_dword v29, v[30:31]
	s_waitcnt vmcnt(0) lgkmcnt(0)
	ds_write_b32 v28, v29 offset:3960
	v_add_u32_e32 v28, 0x1080, v28
	s_cbranch_scc1 .LBB0_278
	s_waitcnt lgkmcnt(0)
	ds_read2_b32 v[26:27], v3 offset1:33
	s_ashr_i32 s23, s22, 31
	s_waitcnt lgkmcnt(0)
	v_cvt_pk_bf16_f32 v26, v26, v27
	ds_read2_b32 v[28:29], v3 offset0:66 offset1:99
	v_add_u32_e32 v4, s26, v1
	v_lshl_add_u64 v[32:33], s[22:23], 1, v[20:21]
	s_waitcnt lgkmcnt(0)
	v_cvt_pk_bf16_f32 v27, v28, v29
	ds_read2_b32 v[28:29], v3 offset0:132 offset1:165
	v_mad_i64_i32 v[38:39], s[22:23], v4, s57, v[32:33]
	s_waitcnt lgkmcnt(0)
	v_cvt_pk_bf16_f32 v28, v28, v29
	ds_read2_b32 v[30:31], v3 offset0:198 offset1:231
	s_waitcnt lgkmcnt(0)
	v_cvt_pk_bf16_f32 v29, v30, v31
	flat_store_dwordx4 v[38:39], v[26:29] sc1
	ds_read2_b32 v[26:27], v3 offset0:8 offset1:41
	v_add_u32_e32 v4, s26, v9
	s_waitcnt lgkmcnt(0)
	v_cvt_pk_bf16_f32 v26, v26, v27
	ds_read2_b32 v[28:29], v3 offset0:74 offset1:107
	s_waitcnt lgkmcnt(0)
	v_cvt_pk_bf16_f32 v27, v28, v29
	ds_read2_b32 v[28:29], v3 offset0:140 offset1:173
	v_mad_i64_i32 v[38:39], s[22:23], v4, s57, v[32:33]
	s_waitcnt lgkmcnt(0)
	v_cvt_pk_bf16_f32 v28, v28, v29
	ds_read2_b32 v[30:31], v3 offset0:206 offset1:239
	s_waitcnt lgkmcnt(0)
	v_cvt_pk_bf16_f32 v29, v30, v31
	flat_store_dwordx4 v[38:39], v[26:29] sc1
	ds_read2_b32 v[26:27], v3 offset0:16 offset1:49
	v_add_u32_e32 v4, s26, v34
	s_waitcnt lgkmcnt(0)
	v_cvt_pk_bf16_f32 v26, v26, v27
	ds_read2_b32 v[28:29], v3 offset0:82 offset1:115
	s_waitcnt lgkmcnt(0)
	v_cvt_pk_bf16_f32 v27, v28, v29
	ds_read2_b32 v[28:29], v3 offset0:148 offset1:181
	v_mad_i64_i32 v[38:39], s[22:23], v4, s57, v[32:33]
	s_waitcnt lgkmcnt(0)
	v_cvt_pk_bf16_f32 v28, v28, v29
	ds_read2_b32 v[30:31], v3 offset0:214 offset1:247
	s_waitcnt lgkmcnt(0)
	v_cvt_pk_bf16_f32 v29, v30, v31
	flat_store_dwordx4 v[38:39], v[26:29] sc1
	ds_read2_b32 v[26:27], v3 offset0:24 offset1:57
	v_add_u32_e32 v4, s26, v35
	s_waitcnt lgkmcnt(0)
	v_cvt_pk_bf16_f32 v26, v26, v27
	ds_read2_b32 v[28:29], v3 offset0:90 offset1:123
	s_waitcnt lgkmcnt(0)
	v_cvt_pk_bf16_f32 v27, v28, v29
	ds_read2_b32 v[28:29], v3 offset0:156 offset1:189
	s_waitcnt lgkmcnt(0)
	v_cvt_pk_bf16_f32 v28, v28, v29
	ds_read2_b32 v[30:31], v3 offset0:222 offset1:255
	s_waitcnt lgkmcnt(0)
	v_cvt_pk_bf16_f32 v29, v30, v31
	v_mad_i64_i32 v[30:31], s[22:23], v4, s57, v[32:33]
	flat_store_dwordx4 v[30:31], v[26:29] sc1
	s_waitcnt lgkmcnt(0)
	s_mov_b32 s26, s10
	s_andn2_b64 vcc, exec, s[8:9]
	s_cbranch_vccnz .LBB0_27

.LBB0_285:
	v_add_u32_e32 v30, s23, v28
	v_ashrrev_i32_e32 v31, 31, v30
	v_lshlrev_b64 v[32:33], 12, v[30:31]
	v_lshl_add_u64 v[32:33], v[26:27], 0, v[32:33]
	flat_load_dword v31, v[32:33]
	v_add_u32_e32 v32, 2, v30
	v_ashrrev_i32_e32 v33, 31, v32
	v_lshlrev_b64 v[32:33], 12, v[32:33]
	v_lshl_add_u64 v[32:33], v[26:27], 0, v[32:33]
	s_add_i32 s23, s23, 32
	s_cmp_lg_u32 s23, 64
	s_waitcnt vmcnt(0) lgkmcnt(0)
	ds_write_b32 v29, v31
	flat_load_dword v31, v[32:33]
	v_add_u32_e32 v32, 4, v30
	v_ashrrev_i32_e32 v33, 31, v32
	v_lshlrev_b64 v[32:33], 12, v[32:33]
	v_lshl_add_u64 v[32:33], v[26:27], 0, v[32:33]
	s_waitcnt vmcnt(0) lgkmcnt(0)
	ds_write_b32 v29, v31 offset:264
	flat_load_dword v31, v[32:33]
	v_add_u32_e32 v32, 6, v30
	v_ashrrev_i32_e32 v33, 31, v32
	v_lshlrev_b64 v[32:33], 12, v[32:33]
	v_lshl_add_u64 v[32:33], v[26:27], 0, v[32:33]
	s_waitcnt vmcnt(0) lgkmcnt(0)
	ds_write_b32 v29, v31 offset:528
	flat_load_dword v31, v[32:33]
	v_add_u32_e32 v32, 8, v30
	v_ashrrev_i32_e32 v33, 31, v32
	v_lshlrev_b64 v[32:33], 12, v[32:33]
	v_lshl_add_u64 v[32:33], v[26:27], 0, v[32:33]
	s_waitcnt vmcnt(0) lgkmcnt(0)
	ds_write_b32 v29, v31 offset:792
	flat_load_dword v31, v[32:33]
	v_add_u32_e32 v32, 10, v30
	v_ashrrev_i32_e32 v33, 31, v32
	v_lshlrev_b64 v[32:33], 12, v[32:33]
	v_lshl_add_u64 v[32:33], v[26:27], 0, v[32:33]
	s_waitcnt vmcnt(0) lgkmcnt(0)
	ds_write_b32 v29, v31 offset:1056
	flat_load_dword v31, v[32:33]
	v_add_u32_e32 v32, 12, v30
	v_ashrrev_i32_e32 v33, 31, v32
	v_lshlrev_b64 v[32:33], 12, v[32:33]
	v_lshl_add_u64 v[32:33], v[26:27], 0, v[32:33]
	s_waitcnt vmcnt(0) lgkmcnt(0)
	ds_write_b32 v29, v31 offset:1320
	flat_load_dword v31, v[32:33]
	v_add_u32_e32 v32, 14, v30
	v_ashrrev_i32_e32 v33, 31, v32
	v_lshlrev_b64 v[32:33], 12, v[32:33]
	v_lshl_add_u64 v[32:33], v[26:27], 0, v[32:33]
	s_waitcnt vmcnt(0) lgkmcnt(0)
	ds_write_b32 v29, v31 offset:1584
	flat_load_dword v31, v[32:33]
	v_add_u32_e32 v32, 16, v30
	v_ashrrev_i32_e32 v33, 31, v32
	v_lshlrev_b64 v[32:33], 12, v[32:33]
	v_lshl_add_u64 v[32:33], v[26:27], 0, v[32:33]
	s_waitcnt vmcnt(0) lgkmcnt(0)
	ds_write_b32 v29, v31 offset:1848
	flat_load_dword v31, v[32:33]
	v_add_u32_e32 v32, 18, v30
	v_ashrrev_i32_e32 v33, 31, v32
	v_lshlrev_b64 v[32:33], 12, v[32:33]
	v_lshl_add_u64 v[32:33], v[26:27], 0, v[32:33]
	s_waitcnt vmcnt(0) lgkmcnt(0)
	ds_write_b32 v29, v31 offset:2112
	flat_load_dword v31, v[32:33]
	v_add_u32_e32 v32, 20, v30
	v_ashrrev_i32_e32 v33, 31, v32
	v_lshlrev_b64 v[32:33], 12, v[32:33]
	v_lshl_add_u64 v[32:33], v[26:27], 0, v[32:33]
	s_waitcnt vmcnt(0) lgkmcnt(0)
	ds_write_b32 v29, v31 offset:2376
	flat_load_dword v31, v[32:33]
	v_add_u32_e32 v32, 22, v30
	v_ashrrev_i32_e32 v33, 31, v32
	v_lshlrev_b64 v[32:33], 12, v[32:33]
	v_lshl_add_u64 v[32:33], v[26:27], 0, v[32:33]
	s_waitcnt vmcnt(0) lgkmcnt(0)
	ds_write_b32 v29, v31 offset:2640
	flat_load_dword v31, v[32:33]
	v_add_u32_e32 v32, 24, v30
	v_ashrrev_i32_e32 v33, 31, v32
	v_lshlrev_b64 v[32:33], 12, v[32:33]
	v_lshl_add_u64 v[32:33], v[26:27], 0, v[32:33]
	s_waitcnt vmcnt(0) lgkmcnt(0)
	ds_write_b32 v29, v31 offset:2904
	flat_load_dword v31, v[32:33]
	v_add_u32_e32 v32, 26, v30
	v_ashrrev_i32_e32 v33, 31, v32
	v_lshlrev_b64 v[32:33], 12, v[32:33]
	v_lshl_add_u64 v[32:33], v[26:27], 0, v[32:33]
	s_waitcnt vmcnt(0) lgkmcnt(0)
	ds_write_b32 v29, v31 offset:3168
	flat_load_dword v31, v[32:33]
	v_add_u32_e32 v32, 28, v30
	v_ashrrev_i32_e32 v33, 31, v32
	v_lshlrev_b64 v[32:33], 12, v[32:33]
	v_lshl_add_u64 v[32:33], v[26:27], 0, v[32:33]
	v_add_u32_e32 v30, 30, v30
	s_waitcnt vmcnt(0) lgkmcnt(0)
	ds_write_b32 v29, v31 offset:3432
	flat_load_dword v32, v[32:33]
	v_ashrrev_i32_e32 v31, 31, v30
	v_lshlrev_b64 v[30:31], 12, v[30:31]
	v_lshl_add_u64 v[30:31], v[26:27], 0, v[30:31]
	s_waitcnt vmcnt(0) lgkmcnt(0)
	ds_write_b32 v29, v32 offset:3696
	flat_load_dword v30, v[30:31]
	s_waitcnt vmcnt(0) lgkmcnt(0)
	ds_write_b32 v29, v30 offset:3960
	v_add_u32_e32 v29, 0x1080, v29
	s_cbranch_scc1 .LBB0_285
	s_lshl_b32 s10, s10, 6
	s_and_b32 s22, s22, 0x1e0
	s_and_b32 s10, s10, 0xfffffc00
	s_or_b32 s10, s10, s22
	s_waitcnt lgkmcnt(0)
	v_or_b32_e32 v38, s10, v1
	ds_read2_b32 v[26:27], v3 offset1:33
	s_ashr_i32 s25, s24, 31
	v_ashrrev_i32_e32 v39, 31, v38
	s_waitcnt lgkmcnt(0)
	v_cvt_pk_bf16_f32 v26, v26, v27
	ds_read2_b32 v[28:29], v3 offset0:66 offset1:99
	v_lshl_add_u64 v[30:31], s[24:25], 1, v[22:23]
	v_lshlrev_b64 v[38:39], 9, v[38:39]
	s_waitcnt lgkmcnt(0)
	v_cvt_pk_bf16_f32 v27, v28, v29
	ds_read2_b32 v[28:29], v3 offset0:132 offset1:165
	v_lshl_add_u64 v[38:39], v[30:31], 0, v[38:39]
	s_waitcnt lgkmcnt(0)
	v_cvt_pk_bf16_f32 v28, v28, v29
	ds_read2_b32 v[32:33], v3 offset0:198 offset1:231
	s_waitcnt lgkmcnt(0)
	v_cvt_pk_bf16_f32 v29, v32, v33
	flat_store_dwordx4 v[38:39], v[26:29] sc1
	v_or_b32_e32 v38, s10, v9
	ds_read2_b32 v[26:27], v3 offset0:8 offset1:41
	v_ashrrev_i32_e32 v39, 31, v38
	s_waitcnt lgkmcnt(0)
	v_cvt_pk_bf16_f32 v26, v26, v27
	ds_read2_b32 v[28:29], v3 offset0:74 offset1:107
	v_lshlrev_b64 v[38:39], 9, v[38:39]
	s_waitcnt lgkmcnt(0)
	v_cvt_pk_bf16_f32 v27, v28, v29
	ds_read2_b32 v[28:29], v3 offset0:140 offset1:173
	v_lshl_add_u64 v[38:39], v[30:31], 0, v[38:39]
	s_waitcnt lgkmcnt(0)
	v_cvt_pk_bf16_f32 v28, v28, v29
	ds_read2_b32 v[32:33], v3 offset0:206 offset1:239
	s_waitcnt lgkmcnt(0)
	v_cvt_pk_bf16_f32 v29, v32, v33
	flat_store_dwordx4 v[38:39], v[26:29] sc1
	v_or_b32_e32 v38, s10, v34
	ds_read2_b32 v[26:27], v3 offset0:16 offset1:49
	v_ashrrev_i32_e32 v39, 31, v38
	s_waitcnt lgkmcnt(0)
	v_cvt_pk_bf16_f32 v26, v26, v27
	ds_read2_b32 v[28:29], v3 offset0:82 offset1:115
	v_lshlrev_b64 v[38:39], 9, v[38:39]
	s_waitcnt lgkmcnt(0)
	v_cvt_pk_bf16_f32 v27, v28, v29
	ds_read2_b32 v[28:29], v3 offset0:148 offset1:181
	v_lshl_add_u64 v[38:39], v[30:31], 0, v[38:39]
	s_waitcnt lgkmcnt(0)
	v_cvt_pk_bf16_f32 v28, v28, v29
	ds_read2_b32 v[32:33], v3 offset0:214 offset1:247
	s_waitcnt lgkmcnt(0)
	v_cvt_pk_bf16_f32 v29, v32, v33
	flat_store_dwordx4 v[38:39], v[26:29] sc1
	v_or_b32_e32 v38, s10, v35
	ds_read2_b32 v[26:27], v3 offset0:24 offset1:57
	v_ashrrev_i32_e32 v39, 31, v38
	s_waitcnt lgkmcnt(0)
	v_cvt_pk_bf16_f32 v26, v26, v27
	ds_read2_b32 v[28:29], v3 offset0:90 offset1:123
	v_lshlrev_b64 v[38:39], 9, v[38:39]
	s_waitcnt lgkmcnt(0)
	v_cvt_pk_bf16_f32 v27, v28, v29
	ds_read2_b32 v[28:29], v3 offset0:156 offset1:189
	v_lshl_add_u64 v[30:31], v[30:31], 0, v[38:39]
	s_waitcnt lgkmcnt(0)
	v_cvt_pk_bf16_f32 v28, v28, v29
	ds_read2_b32 v[32:33], v3 offset0:222 offset1:255
	s_waitcnt lgkmcnt(0)
	v_cvt_pk_bf16_f32 v29, v32, v33
	flat_store_dwordx4 v[30:31], v[26:29] sc1
	s_waitcnt lgkmcnt(0)
	s_mov_b32 s10, s26
	s_andn2_b64 vcc, exec, s[8:9]
	s_cbranch_vccnz .LBB0_27

.LBB0_289:
	v_add_u32_e32 v30, s23, v28
	v_ashrrev_i32_e32 v31, 31, v30
	v_lshlrev_b64 v[32:33], 12, v[30:31]
	v_lshl_add_u64 v[32:33], v[26:27], 0, v[32:33]
	flat_load_dword v31, v[32:33]
	v_add_u32_e32 v32, 2, v30
	v_ashrrev_i32_e32 v33, 31, v32
	v_lshlrev_b64 v[32:33], 12, v[32:33]
	v_lshl_add_u64 v[32:33], v[26:27], 0, v[32:33]
	s_add_i32 s23, s23, 32
	s_cmp_lg_u32 s23, 64
	s_waitcnt vmcnt(0) lgkmcnt(0)
	ds_write_b32 v29, v31
	flat_load_dword v31, v[32:33]
	v_add_u32_e32 v32, 4, v30
	v_ashrrev_i32_e32 v33, 31, v32
	v_lshlrev_b64 v[32:33], 12, v[32:33]
	v_lshl_add_u64 v[32:33], v[26:27], 0, v[32:33]
	s_waitcnt vmcnt(0) lgkmcnt(0)
	ds_write_b32 v29, v31 offset:264
	flat_load_dword v31, v[32:33]
	v_add_u32_e32 v32, 6, v30
	v_ashrrev_i32_e32 v33, 31, v32
	v_lshlrev_b64 v[32:33], 12, v[32:33]
	v_lshl_add_u64 v[32:33], v[26:27], 0, v[32:33]
	s_waitcnt vmcnt(0) lgkmcnt(0)
	ds_write_b32 v29, v31 offset:528
	flat_load_dword v31, v[32:33]
	v_add_u32_e32 v32, 8, v30
	v_ashrrev_i32_e32 v33, 31, v32
	v_lshlrev_b64 v[32:33], 12, v[32:33]
	v_lshl_add_u64 v[32:33], v[26:27], 0, v[32:33]
	s_waitcnt vmcnt(0) lgkmcnt(0)
	ds_write_b32 v29, v31 offset:792
	flat_load_dword v31, v[32:33]
	v_add_u32_e32 v32, 10, v30
	v_ashrrev_i32_e32 v33, 31, v32
	v_lshlrev_b64 v[32:33], 12, v[32:33]
	v_lshl_add_u64 v[32:33], v[26:27], 0, v[32:33]
	s_waitcnt vmcnt(0) lgkmcnt(0)
	ds_write_b32 v29, v31 offset:1056
	flat_load_dword v31, v[32:33]
	v_add_u32_e32 v32, 12, v30
	v_ashrrev_i32_e32 v33, 31, v32
	v_lshlrev_b64 v[32:33], 12, v[32:33]
	v_lshl_add_u64 v[32:33], v[26:27], 0, v[32:33]
	s_waitcnt vmcnt(0) lgkmcnt(0)
	ds_write_b32 v29, v31 offset:1320
	flat_load_dword v31, v[32:33]
	v_add_u32_e32 v32, 14, v30
	v_ashrrev_i32_e32 v33, 31, v32
	v_lshlrev_b64 v[32:33], 12, v[32:33]
	v_lshl_add_u64 v[32:33], v[26:27], 0, v[32:33]
	s_waitcnt vmcnt(0) lgkmcnt(0)
	ds_write_b32 v29, v31 offset:1584
	flat_load_dword v31, v[32:33]
	v_add_u32_e32 v32, 16, v30
	v_ashrrev_i32_e32 v33, 31, v32
	v_lshlrev_b64 v[32:33], 12, v[32:33]
	v_lshl_add_u64 v[32:33], v[26:27], 0, v[32:33]
	s_waitcnt vmcnt(0) lgkmcnt(0)
	ds_write_b32 v29, v31 offset:1848
	flat_load_dword v31, v[32:33]
	v_add_u32_e32 v32, 18, v30
	v_ashrrev_i32_e32 v33, 31, v32
	v_lshlrev_b64 v[32:33], 12, v[32:33]
	v_lshl_add_u64 v[32:33], v[26:27], 0, v[32:33]
	s_waitcnt vmcnt(0) lgkmcnt(0)
	ds_write_b32 v29, v31 offset:2112
	flat_load_dword v31, v[32:33]
	v_add_u32_e32 v32, 20, v30
	v_ashrrev_i32_e32 v33, 31, v32
	v_lshlrev_b64 v[32:33], 12, v[32:33]
	v_lshl_add_u64 v[32:33], v[26:27], 0, v[32:33]
	s_waitcnt vmcnt(0) lgkmcnt(0)
	ds_write_b32 v29, v31 offset:2376
	flat_load_dword v31, v[32:33]
	v_add_u32_e32 v32, 22, v30
	v_ashrrev_i32_e32 v33, 31, v32
	v_lshlrev_b64 v[32:33], 12, v[32:33]
	v_lshl_add_u64 v[32:33], v[26:27], 0, v[32:33]
	s_waitcnt vmcnt(0) lgkmcnt(0)
	ds_write_b32 v29, v31 offset:2640
	flat_load_dword v31, v[32:33]
	v_add_u32_e32 v32, 24, v30
	v_ashrrev_i32_e32 v33, 31, v32
	v_lshlrev_b64 v[32:33], 12, v[32:33]
	v_lshl_add_u64 v[32:33], v[26:27], 0, v[32:33]
	s_waitcnt vmcnt(0) lgkmcnt(0)
	ds_write_b32 v29, v31 offset:2904
	flat_load_dword v31, v[32:33]
	v_add_u32_e32 v32, 26, v30
	v_ashrrev_i32_e32 v33, 31, v32
	v_lshlrev_b64 v[32:33], 12, v[32:33]
	v_lshl_add_u64 v[32:33], v[26:27], 0, v[32:33]
	s_waitcnt vmcnt(0) lgkmcnt(0)
	ds_write_b32 v29, v31 offset:3168
	flat_load_dword v31, v[32:33]
	v_add_u32_e32 v32, 28, v30
	v_ashrrev_i32_e32 v33, 31, v32
	v_lshlrev_b64 v[32:33], 12, v[32:33]
	v_lshl_add_u64 v[32:33], v[26:27], 0, v[32:33]
	v_add_u32_e32 v30, 30, v30
	s_waitcnt vmcnt(0) lgkmcnt(0)
	ds_write_b32 v29, v31 offset:3432
	flat_load_dword v32, v[32:33]
	v_ashrrev_i32_e32 v31, 31, v30
	v_lshlrev_b64 v[30:31], 12, v[30:31]
	v_lshl_add_u64 v[30:31], v[26:27], 0, v[30:31]
	s_waitcnt vmcnt(0) lgkmcnt(0)
	ds_write_b32 v29, v32 offset:3696
	flat_load_dword v30, v[30:31]
	s_waitcnt vmcnt(0) lgkmcnt(0)
	ds_write_b32 v29, v30 offset:3960
	v_add_u32_e32 v29, 0x1080, v29
	s_cbranch_scc1 .LBB0_289
	s_lshl_b32 s23, s25, 6
	s_and_b32 s22, s22, 0x1e0
	s_and_b32 s23, s23, 0xfffffc00
	s_or_b32 s22, s22, s23
	s_bitset1_b32 s22, 9
	s_waitcnt lgkmcnt(0)
	v_or_b32_e32 v38, s22, v1
	ds_read2_b32 v[26:27], v3 offset1:33
	s_ashr_i32 s25, s24, 31
	v_ashrrev_i32_e32 v39, 31, v38
	s_waitcnt lgkmcnt(0)
	v_cvt_pk_bf16_f32 v26, v26, v27
	ds_read2_b32 v[28:29], v3 offset0:66 offset1:99
	v_lshl_add_u64 v[30:31], s[24:25], 1, v[22:23]
	v_lshlrev_b64 v[38:39], 9, v[38:39]
	s_waitcnt lgkmcnt(0)
	v_cvt_pk_bf16_f32 v27, v28, v29
	ds_read2_b32 v[28:29], v3 offset0:132 offset1:165
	v_lshl_add_u64 v[38:39], v[30:31], 0, v[38:39]
	s_waitcnt lgkmcnt(0)
	v_cvt_pk_bf16_f32 v28, v28, v29
	ds_read2_b32 v[32:33], v3 offset0:198 offset1:231
	s_waitcnt lgkmcnt(0)
	v_cvt_pk_bf16_f32 v29, v32, v33
	flat_store_dwordx4 v[38:39], v[26:29] sc1
	v_or_b32_e32 v38, s22, v9
	ds_read2_b32 v[26:27], v3 offset0:8 offset1:41
	v_ashrrev_i32_e32 v39, 31, v38
	s_waitcnt lgkmcnt(0)
	v_cvt_pk_bf16_f32 v26, v26, v27
	ds_read2_b32 v[28:29], v3 offset0:74 offset1:107
	v_lshlrev_b64 v[38:39], 9, v[38:39]
	s_waitcnt lgkmcnt(0)
	v_cvt_pk_bf16_f32 v27, v28, v29
	ds_read2_b32 v[28:29], v3 offset0:140 offset1:173
	v_lshl_add_u64 v[38:39], v[30:31], 0, v[38:39]
	s_waitcnt lgkmcnt(0)
	v_cvt_pk_bf16_f32 v28, v28, v29
	ds_read2_b32 v[32:33], v3 offset0:206 offset1:239
	s_waitcnt lgkmcnt(0)
	v_cvt_pk_bf16_f32 v29, v32, v33
	flat_store_dwordx4 v[38:39], v[26:29] sc1
	v_or_b32_e32 v38, s22, v34
	ds_read2_b32 v[26:27], v3 offset0:16 offset1:49
	v_ashrrev_i32_e32 v39, 31, v38
	s_waitcnt lgkmcnt(0)
	v_cvt_pk_bf16_f32 v26, v26, v27
	ds_read2_b32 v[28:29], v3 offset0:82 offset1:115
	v_lshlrev_b64 v[38:39], 9, v[38:39]
	s_waitcnt lgkmcnt(0)
	v_cvt_pk_bf16_f32 v27, v28, v29
	ds_read2_b32 v[28:29], v3 offset0:148 offset1:181
	v_lshl_add_u64 v[38:39], v[30:31], 0, v[38:39]
	s_waitcnt lgkmcnt(0)
	v_cvt_pk_bf16_f32 v28, v28, v29
	ds_read2_b32 v[32:33], v3 offset0:214 offset1:247
	s_waitcnt lgkmcnt(0)
	v_cvt_pk_bf16_f32 v29, v32, v33
	flat_store_dwordx4 v[38:39], v[26:29] sc1
	v_or_b32_e32 v38, s22, v35
	ds_read2_b32 v[26:27], v3 offset0:24 offset1:57
	v_ashrrev_i32_e32 v39, 31, v38
	s_waitcnt lgkmcnt(0)
	v_cvt_pk_bf16_f32 v26, v26, v27
	ds_read2_b32 v[28:29], v3 offset0:90 offset1:123
	v_lshlrev_b64 v[38:39], 9, v[38:39]
	s_waitcnt lgkmcnt(0)
	v_cvt_pk_bf16_f32 v27, v28, v29
	ds_read2_b32 v[28:29], v3 offset0:156 offset1:189
	v_lshl_add_u64 v[30:31], v[30:31], 0, v[38:39]
	s_waitcnt lgkmcnt(0)
	v_cvt_pk_bf16_f32 v28, v28, v29
	ds_read2_b32 v[32:33], v3 offset0:222 offset1:255
	s_waitcnt lgkmcnt(0)
	v_cvt_pk_bf16_f32 v29, v32, v33
	flat_store_dwordx4 v[30:31], v[26:29] sc1
	s_waitcnt lgkmcnt(0)
	s_mov_b64 s[22:23], 0

.LBB0_295:
	v_add_u32_e32 v30, s9, v4
	v_ashrrev_i32_e32 v31, 31, v30
	v_lshlrev_b64 v[32:33], 12, v[30:31]
	v_lshl_add_u64 v[32:33], v[26:27], 0, v[32:33]
	global_load_dword v184, v[32:33], off
	v_add_u32_e32 v32, 2, v30
	v_ashrrev_i32_e32 v33, 31, v32
	v_lshlrev_b64 v[32:33], 12, v[32:33]
	v_lshl_add_u64 v[32:33], v[26:27], 0, v[32:33]
	s_add_i32 s9, s9, 32
	s_cmp_lg_u32 s9, 64
	global_load_dword v185, v[32:33], off
	v_add_u32_e32 v32, 4, v30
	v_ashrrev_i32_e32 v33, 31, v32
	v_lshlrev_b64 v[32:33], 12, v[32:33]
	v_lshl_add_u64 v[32:33], v[26:27], 0, v[32:33]
	global_load_dword v186, v[32:33], off
	v_add_u32_e32 v32, 6, v30
	v_ashrrev_i32_e32 v33, 31, v32
	v_lshlrev_b64 v[32:33], 12, v[32:33]
	v_lshl_add_u64 v[32:33], v[26:27], 0, v[32:33]
	global_load_dword v187, v[32:33], off
	v_add_u32_e32 v32, 8, v30
	v_ashrrev_i32_e32 v33, 31, v32
	v_lshlrev_b64 v[32:33], 12, v[32:33]
	v_lshl_add_u64 v[32:33], v[26:27], 0, v[32:33]
	global_load_dword v188, v[32:33], off
	v_add_u32_e32 v32, 10, v30
	v_ashrrev_i32_e32 v33, 31, v32
	v_lshlrev_b64 v[32:33], 12, v[32:33]
	v_lshl_add_u64 v[32:33], v[26:27], 0, v[32:33]
	global_load_dword v189, v[32:33], off
	v_add_u32_e32 v32, 12, v30
	v_ashrrev_i32_e32 v33, 31, v32
	v_lshlrev_b64 v[32:33], 12, v[32:33]
	v_lshl_add_u64 v[32:33], v[26:27], 0, v[32:33]
	global_load_dword v190, v[32:33], off
	v_add_u32_e32 v32, 14, v30
	v_ashrrev_i32_e32 v33, 31, v32
	v_lshlrev_b64 v[32:33], 12, v[32:33]
	v_lshl_add_u64 v[32:33], v[26:27], 0, v[32:33]
	global_load_dword v191, v[32:33], off
	v_add_u32_e32 v32, 16, v30
	v_ashrrev_i32_e32 v33, 31, v32
	v_lshlrev_b64 v[32:33], 12, v[32:33]
	v_lshl_add_u64 v[32:33], v[26:27], 0, v[32:33]
	global_load_dword v192, v[32:33], off
	v_add_u32_e32 v32, 18, v30
	v_ashrrev_i32_e32 v33, 31, v32
	v_lshlrev_b64 v[32:33], 12, v[32:33]
	v_lshl_add_u64 v[32:33], v[26:27], 0, v[32:33]
	global_load_dword v193, v[32:33], off
	v_add_u32_e32 v32, 20, v30
	v_ashrrev_i32_e32 v33, 31, v32
	v_lshlrev_b64 v[32:33], 12, v[32:33]
	v_lshl_add_u64 v[32:33], v[26:27], 0, v[32:33]
	global_load_dword v194, v[32:33], off
	v_add_u32_e32 v32, 22, v30
	v_ashrrev_i32_e32 v33, 31, v32
	v_lshlrev_b64 v[32:33], 12, v[32:33]
	v_lshl_add_u64 v[32:33], v[26:27], 0, v[32:33]
	global_load_dword v195, v[32:33], off
	v_add_u32_e32 v32, 24, v30
	v_ashrrev_i32_e32 v33, 31, v32
	v_lshlrev_b64 v[32:33], 12, v[32:33]
	v_lshl_add_u64 v[32:33], v[26:27], 0, v[32:33]
	global_load_dword v196, v[32:33], off
	v_add_u32_e32 v32, 26, v30
	v_ashrrev_i32_e32 v33, 31, v32
	v_lshlrev_b64 v[32:33], 12, v[32:33]
	v_lshl_add_u64 v[32:33], v[26:27], 0, v[32:33]
	global_load_dword v197, v[32:33], off
	v_add_u32_e32 v32, 28, v30
	v_ashrrev_i32_e32 v33, 31, v32
	v_lshlrev_b64 v[32:33], 12, v[32:33]
	v_lshl_add_u64 v[32:33], v[26:27], 0, v[32:33]
	v_add_u32_e32 v30, 30, v30
	v_ashrrev_i32_e32 v31, 31, v30
	v_lshlrev_b64 v[30:31], 12, v[30:31]
	v_lshl_add_u64 v[30:31], v[26:27], 0, v[30:31]
	global_load_dword v198, v[32:33], off
	global_load_dword v199, v[30:31], off
	s_waitcnt vmcnt(0)
	ds_write_b32 v28, v184
	ds_write_b32 v28, v185 offset:264
	ds_write_b32 v28, v186 offset:528
	ds_write_b32 v28, v187 offset:792
	ds_write_b32 v28, v188 offset:1056
	ds_write_b32 v28, v189 offset:1320
	ds_write_b32 v28, v190 offset:1584
	ds_write_b32 v28, v191 offset:1848
	ds_write_b32 v28, v192 offset:2112
	ds_write_b32 v28, v193 offset:2376
	ds_write_b32 v28, v194 offset:2640
	ds_write_b32 v28, v195 offset:2904
	ds_write_b32 v28, v196 offset:3168
	ds_write_b32 v28, v197 offset:3432
	ds_write_b32 v28, v198 offset:3696
	ds_write_b32 v28, v199 offset:3960
	v_add_u32_e32 v28, 0x1080, v28
	s_cbranch_scc1 .LBB0_295
	s_waitcnt lgkmcnt(0)
	ds_read2_b32 v[26:27], v3 offset1:33
	v_or_b32_e32 v30, s8, v1
	s_waitcnt lgkmcnt(0)
	v_cvt_pk_bf16_f32 v26, v26, v27
	ds_read2_b32 v[28:29], v3 offset0:66 offset1:99
	s_ashr_i32 s23, s22, 31
	v_ashrrev_i32_e32 v31, 31, v30
	s_waitcnt lgkmcnt(0)
	v_cvt_pk_bf16_f32 v27, v28, v29
	ds_read2_b32 v[28:29], v3 offset0:132 offset1:165
	v_lshl_add_u64 v[38:39], s[22:23], 1, v[24:25]
	v_lshlrev_b64 v[30:31], 11, v[30:31]
	s_waitcnt lgkmcnt(0)
	v_cvt_pk_bf16_f32 v28, v28, v29
	ds_read2_b32 v[32:33], v3 offset0:198 offset1:231
	v_lshl_add_u64 v[30:31], v[38:39], 0, v[30:31]
	s_waitcnt lgkmcnt(0)
	v_cvt_pk_bf16_f32 v29, v32, v33
	flat_store_dwordx4 v[30:31], v[26:29] sc1
	v_or_b32_e32 v32, s8, v9
	ds_read2_b32 v[26:27], v3 offset0:8 offset1:41
	v_ashrrev_i32_e32 v33, 31, v32
	s_waitcnt lgkmcnt(0)
	v_cvt_pk_bf16_f32 v26, v26, v27
	ds_read2_b32 v[28:29], v3 offset0:74 offset1:107
	v_lshlrev_b64 v[32:33], 11, v[32:33]
	s_waitcnt lgkmcnt(0)
	v_cvt_pk_bf16_f32 v27, v28, v29
	ds_read2_b32 v[28:29], v3 offset0:140 offset1:173
	v_lshl_add_u64 v[32:33], v[38:39], 0, v[32:33]
	s_waitcnt lgkmcnt(0)
	v_cvt_pk_bf16_f32 v28, v28, v29
	ds_read2_b32 v[30:31], v3 offset0:206 offset1:239
	s_waitcnt lgkmcnt(0)
	v_cvt_pk_bf16_f32 v29, v30, v31
	flat_store_dwordx4 v[32:33], v[26:29] sc1
	v_or_b32_e32 v32, s8, v34
	ds_read2_b32 v[26:27], v3 offset0:16 offset1:49
	v_ashrrev_i32_e32 v33, 31, v32
	s_waitcnt lgkmcnt(0)
	v_cvt_pk_bf16_f32 v26, v26, v27
	ds_read2_b32 v[28:29], v3 offset0:82 offset1:115
	v_lshlrev_b64 v[32:33], 11, v[32:33]
	s_waitcnt lgkmcnt(0)
	v_cvt_pk_bf16_f32 v27, v28, v29
	ds_read2_b32 v[28:29], v3 offset0:148 offset1:181
	v_lshl_add_u64 v[32:33], v[38:39], 0, v[32:33]
	s_waitcnt lgkmcnt(0)
	v_cvt_pk_bf16_f32 v28, v28, v29
	ds_read2_b32 v[30:31], v3 offset0:214 offset1:247
	s_waitcnt lgkmcnt(0)
	v_cvt_pk_bf16_f32 v29, v30, v31
	flat_store_dwordx4 v[32:33], v[26:29] sc1
	ds_read2_b32 v[26:27], v3 offset0:24 offset1:57
	v_or_b32_e32 v32, s8, v35
	s_waitcnt lgkmcnt(0)
	v_cvt_pk_bf16_f32 v26, v26, v27
	ds_read2_b32 v[28:29], v3 offset0:90 offset1:123
	s_waitcnt lgkmcnt(0)
	v_cvt_pk_bf16_f32 v27, v28, v29
	ds_read2_b32 v[28:29], v3 offset0:156 offset1:189
	v_ashrrev_i32_e32 v33, 31, v32
	s_waitcnt lgkmcnt(0)
	v_cvt_pk_bf16_f32 v28, v28, v29
	ds_read2_b32 v[30:31], v3 offset0:222 offset1:255
	v_lshlrev_b64 v[32:33], 11, v[32:33]
	s_waitcnt lgkmcnt(0)
	v_cvt_pk_bf16_f32 v29, v30, v31
	v_lshl_add_u64 v[30:31], v[38:39], 0, v[32:33]
	flat_store_dwordx4 v[30:31], v[26:29] sc1
	s_waitcnt lgkmcnt(0)
	s_branch .LBB0_27

.LBB0_307:
	v_add_u32_e32 v6, s12, v6
	v_cmp_lt_i32_e32 vcc, s3, v6
	flat_store_dwordx4 v[4:5], v[0:3] sc1
	s_or_b64 s[10:11], vcc, s[10:11]
	v_lshl_add_u64 v[4:5], v[4:5], 0, s[8:9]
	s_andn2_b64 exec, exec, s[10:11]
	s_cbranch_execnz .LBB0_307

.LBB0_310:
	v_and_b32_e32 v2, 0x3f8, v16
	v_or_b32_e32 v3, 1, v2
	v_or_b32_e32 v6, 2, v2
	v_or_b32_e32 v14, 3, v2
	v_or_b32_e32 v15, 4, v2
	v_or_b32_e32 v24, 5, v2
	v_or_b32_e32 v26, 6, v2
	v_or_b32_e32 v28, 7, v2
	v_mad_u64_u32 v[130:131], s[6:7], v2, s22, v[10:11]
	v_mad_u64_u32 v[4:5], s[6:7], v3, s22, v[10:11]
	v_mad_u64_u32 v[6:7], s[6:7], v6, s22, v[10:11]
	v_mad_u64_u32 v[20:21], s[6:7], v14, s22, v[10:11]
	v_mad_u64_u32 v[22:23], s[6:7], v15, s22, v[10:11]
	v_mad_u64_u32 v[24:25], s[6:7], v24, s22, v[10:11]
	v_mad_u64_u32 v[26:27], s[6:7], v26, s22, v[10:11]
	v_mad_u64_u32 v[28:29], s[6:7], v28, s22, v[10:11]
	v_add_co_u32_e64 v78, s[6:7], s13, v4
	v_ashrrev_i32_e32 v0, 7, v17
	s_nop 0
	v_addc_co_u32_e64 v79, s[6:7], 0, v5, s[6:7]
	v_add_co_u32_e64 v80, s[6:7], s13, v6
	v_add_u32_e32 v17, s12, v17
	s_nop 0
	v_addc_co_u32_e64 v81, s[6:7], 0, v7, s[6:7]
	v_add_co_u32_e64 v82, s[6:7], s13, v20
	v_ashrrev_i32_e32 v1, 31, v0
	s_nop 0
	v_addc_co_u32_e64 v83, s[6:7], 0, v21, s[6:7]
	v_add_co_u32_e64 v106, s[6:7], s13, v22
	v_cmp_lt_i32_e32 vcc, s8, v17
	s_nop 0
	v_addc_co_u32_e64 v107, s[6:7], 0, v23, s[6:7]
	v_add_co_u32_e64 v108, s[6:7], s13, v24
	v_lshl_add_u64 v[132:133], v[0:1], 2, s[10:11]
	s_nop 0
	v_addc_co_u32_e64 v109, s[6:7], 0, v25, s[6:7]
	s_or_b64 s[20:21], vcc, s[20:21]
	v_add_co_u32_e32 v134, vcc, 0x1000, v132
	v_add_co_u32_e64 v110, s[6:7], s13, v26
	s_nop 0
	v_addc_co_u32_e32 v135, vcc, 0, v133, vcc
	v_addc_co_u32_e64 v111, s[6:7], 0, v27, s[6:7]
	v_lshlrev_b32_e32 v12, 2, v2
	v_add_co_u32_e64 v126, s[6:7], s13, v28
	v_add_co_u32_e32 v138, vcc, 0x2000, v132
	v_lshl_add_u64 v[18:19], s[16:17], 0, v[12:13]
	v_lshlrev_b64 v[30:31], 11, v[0:1]
	v_addc_co_u32_e64 v127, s[6:7], 0, v29, s[6:7]
	v_addc_co_u32_e32 v139, vcc, 0, v133, vcc
	v_lshlrev_b32_e32 v12, 1, v2
	flat_load_dword v14, v[132:133]
	flat_load_dword v146, v[132:133] offset:2048
	flat_load_dwordx4 v[0:3], v[18:19]
	flat_load_dwordx4 v[4:7], v[18:19] offset:16
	v_lshl_add_u64 v[136:137], s[18:19], 0, v[30:31]
	flat_load_dwordx4 v[18:21], v[78:79]
	flat_load_dwordx4 v[22:25], v[78:79] offset:16
	flat_load_dwordx4 v[26:29], v[78:79] offset:32
	flat_load_dwordx4 v[30:33], v[78:79] offset:48
	flat_load_dwordx4 v[34:37], v[80:81]
	flat_load_dwordx4 v[38:41], v[80:81] offset:16
	flat_load_dwordx4 v[42:45], v[80:81] offset:32
	flat_load_dwordx4 v[46:49], v[80:81] offset:48
	flat_load_dwordx4 v[50:53], v[82:83]
	flat_load_dwordx4 v[54:57], v[82:83] offset:16
	flat_load_dwordx4 v[58:61], v[82:83] offset:32
	flat_load_dwordx4 v[62:65], v[82:83] offset:48
	flat_load_dwordx4 v[66:69], v[106:107]
	flat_load_dwordx4 v[70:73], v[106:107] offset:16
	flat_load_dwordx4 v[74:77], v[106:107] offset:32
	flat_load_dwordx4 v[78:81], v[106:107] offset:48
	s_nop 0
	flat_load_dwordx4 v[82:85], v[108:109]
	flat_load_dwordx4 v[86:89], v[108:109] offset:16
	flat_load_dwordx4 v[90:93], v[108:109] offset:32
	flat_load_dwordx4 v[94:97], v[108:109] offset:48
	flat_load_dwordx4 v[98:101], v[110:111]
	flat_load_dwordx4 v[102:105], v[110:111] offset:16
	s_nop 0
	flat_load_dwordx4 v[106:109], v[110:111] offset:32
	s_nop 0
	flat_load_dwordx4 v[110:113], v[110:111] offset:48
	s_nop 0
	flat_load_dwordx4 v[114:117], v[126:127]
	flat_load_dwordx4 v[118:121], v[126:127] offset:16
	flat_load_dwordx4 v[122:125], v[126:127] offset:32
	s_nop 0
	flat_load_dwordx4 v[126:129], v[126:127] offset:48
	s_nop 0
	flat_load_dword v150, v[134:135]
	flat_load_dword v152, v[134:135] offset:2048
	v_add_co_u32_e32 v134, vcc, 0x3000, v132
	v_lshl_add_u64 v[148:149], v[136:137], 0, v[12:13]
	s_nop 0
	v_addc_co_u32_e32 v135, vcc, 0, v133, vcc
	v_add_co_u32_e32 v136, vcc, 0x4000, v132
	flat_load_dword v15, v[138:139]
	flat_load_dword v147, v[138:139] offset:2048
	flat_load_dword v151, v[134:135]
	flat_load_dword v153, v[134:135] offset:2048
	v_addc_co_u32_e32 v137, vcc, 0, v133, vcc
	v_add_co_u32_e32 v134, vcc, 0x5000, v132
	v_add_u32_e32 v16, s3, v16
	s_nop 0
	v_addc_co_u32_e32 v135, vcc, 0, v133, vcc
	v_add_co_u32_e32 v138, vcc, 0x6000, v132
	flat_load_dword v154, v[136:137]
	flat_load_dword v156, v[136:137] offset:2048
	flat_load_dword v158, v[134:135]
	flat_load_dword v160, v[134:135] offset:2048
	v_addc_co_u32_e32 v139, vcc, 0, v133, vcc
	v_add_co_u32_e32 v132, vcc, 0x7000, v132
	s_waitcnt vmcnt(0) lgkmcnt(0)
	v_mov_b32_e32 v162, v18
	v_addc_co_u32_e32 v133, vcc, 0, v133, vcc
	v_add_co_u32_e32 v142, vcc, s13, v130
	flat_load_dword v155, v[138:139]
	flat_load_dword v157, v[138:139] offset:2048
	flat_load_dword v159, v[132:133]
	flat_load_dword v161, v[132:133] offset:2048
	v_addc_co_u32_e32 v143, vcc, 0, v131, vcc
	flat_load_dwordx4 v[130:133], v[142:143]
	flat_load_dwordx4 v[134:137], v[142:143] offset:16
	flat_load_dwordx4 v[138:141], v[142:143] offset:32
	s_nop 0
	flat_load_dwordx4 v[142:145], v[142:143] offset:48
	v_mov_b32_e32 v163, v22
	v_mov_b32_e32 v22, v19
	v_mov_b32_e32 v19, v24
	v_mov_b32_e32 v24, v21
	v_mov_b32_e32 v21, v30
	v_mov_b32_e32 v30, v27
	v_mov_b32_e32 v27, v32
	v_mov_b32_e32 v32, v29
	v_mov_b32_e32 v29, v38
	v_mov_b32_e32 v38, v35
	v_mov_b32_e32 v35, v40
	v_mov_b32_e32 v40, v37
	v_mov_b32_e32 v37, v46
	v_mov_b32_e32 v46, v43
	v_mov_b32_e32 v43, v48
	v_mov_b32_e32 v48, v45
	v_mov_b32_e32 v45, v54
	v_mov_b32_e32 v54, v51
	v_mov_b32_e32 v51, v56
	v_mov_b32_e32 v56, v53
	v_mov_b32_e32 v53, v62
	v_mov_b32_e32 v62, v59
	v_mov_b32_e32 v59, v64
	v_mov_b32_e32 v64, v61
	v_mov_b32_e32 v61, v70
	v_mov_b32_e32 v70, v67
	v_mov_b32_e32 v67, v72
	v_mov_b32_e32 v72, v69
	v_mov_b32_e32 v69, v78
	v_mov_b32_e32 v78, v75
	v_mov_b32_e32 v75, v80
	v_mov_b32_e32 v80, v77
	v_mov_b32_e32 v77, v86
	v_mov_b32_e32 v86, v83
	v_mov_b32_e32 v18, v20
	v_mov_b32_e32 v20, v26
	v_mov_b32_e32 v26, v28
	v_mov_b32_e32 v28, v34
	v_mov_b32_e32 v34, v36
	v_mov_b32_e32 v36, v42
	v_mov_b32_e32 v42, v44
	v_mov_b32_e32 v44, v50
	v_mov_b32_e32 v50, v52
	v_mov_b32_e32 v52, v58
	v_mov_b32_e32 v58, v60
	v_mov_b32_e32 v60, v66
	v_mov_b32_e32 v66, v68
	v_mov_b32_e32 v68, v74
	v_mov_b32_e32 v74, v76
	v_mov_b32_e32 v76, v82
	v_mov_b32_e32 v83, v88
	v_mov_b32_e32 v88, v85
	v_mov_b32_e32 v85, v94
	v_mov_b32_e32 v94, v91
	v_mov_b32_e32 v91, v96
	v_mov_b32_e32 v96, v93
	v_mov_b32_e32 v93, v102
	v_mov_b32_e32 v102, v99
	v_pk_mul_f32 v[22:23], v[146:147], v[22:23]
	v_pk_mul_f32 v[38:39], v[146:147], v[38:39]
	v_pk_mul_f32 v[54:55], v[146:147], v[54:55]
	v_pk_mul_f32 v[70:71], v[146:147], v[70:71]
	v_pk_mul_f32 v[86:87], v[146:147], v[86:87]
	v_mov_b32_e32 v82, v84
	v_mov_b32_e32 v84, v90
	v_mov_b32_e32 v90, v92
	v_mov_b32_e32 v92, v98
	v_mov_b32_e32 v99, v104
	v_mov_b32_e32 v104, v101
	v_mov_b32_e32 v101, v110
	v_mov_b32_e32 v110, v107
	v_mov_b32_e32 v107, v112
	v_mov_b32_e32 v112, v109
	v_mov_b32_e32 v109, v118
	v_mov_b32_e32 v118, v115
	v_pk_mul_f32 v[102:103], v[146:147], v[102:103]
	v_pk_fma_f32 v[22:23], v[14:15], v[162:163], v[22:23]
	v_pk_fma_f32 v[28:29], v[14:15], v[28:29], v[38:39]
	v_pk_fma_f32 v[38:39], v[14:15], v[44:45], v[54:55]
	v_pk_fma_f32 v[44:45], v[14:15], v[60:61], v[70:71]
	v_pk_fma_f32 v[54:55], v[14:15], v[76:77], v[86:87]
	v_mov_b32_e32 v98, v100
	v_mov_b32_e32 v100, v106
	v_mov_b32_e32 v106, v108
	v_mov_b32_e32 v108, v114
	v_pk_mul_f32 v[118:119], v[146:147], v[118:119]
	v_pk_fma_f32 v[60:61], v[14:15], v[92:93], v[102:103]
	v_pk_fma_f32 v[18:19], v[150:151], v[18:19], v[22:23]
	v_pk_fma_f32 v[22:23], v[150:151], v[34:35], v[28:29]
	v_pk_fma_f32 v[28:29], v[150:151], v[50:51], v[38:39]
	v_pk_fma_f32 v[34:35], v[150:151], v[66:67], v[44:45]
	v_pk_fma_f32 v[38:39], v[150:151], v[82:83], v[54:55]
	v_mov_b32_e32 v114, v116
	v_mov_b32_e32 v115, v120
	v_mov_b32_e32 v120, v117
	v_mov_b32_e32 v117, v126
	v_mov_b32_e32 v126, v123
	v_pk_fma_f32 v[70:71], v[14:15], v[108:109], v[118:119]
	v_pk_fma_f32 v[44:45], v[150:151], v[98:99], v[60:61]
	v_pk_fma_f32 v[18:19], v[152:153], v[24:25], v[18:19]
	v_pk_fma_f32 v[22:23], v[152:153], v[40:41], v[22:23]
	v_pk_fma_f32 v[24:25], v[152:153], v[56:57], v[28:29]
	v_pk_fma_f32 v[28:29], v[152:153], v[72:73], v[34:35]
	v_pk_fma_f32 v[34:35], v[152:153], v[88:89], v[38:39]
	v_mov_b32_e32 v116, v122
	v_pk_fma_f32 v[50:51], v[150:151], v[114:115], v[70:71]
	v_pk_fma_f32 v[38:39], v[152:153], v[104:105], v[44:45]
	v_add_f32_e32 v12, 0, v18
	s_waitcnt vmcnt(0) lgkmcnt(0)
	v_pk_mul_f32 v[30:31], v[156:157], v[30:31]
	v_add_f32_e32 v22, 0, v22
	v_pk_mul_f32 v[44:45], v[156:157], v[46:47]
	v_pk_mul_f32 v[46:47], v[156:157], v[62:63]
	v_add_f32_e32 v28, 0, v28
	v_add_f32_e32 v34, 0, v34
	v_pk_mul_f32 v[54:55], v[156:157], v[94:95]
	v_pk_mul_f32 v[56:57], v[156:157], v[110:111]
	v_pk_mul_f32 v[60:61], v[156:157], v[126:127]
	v_mov_b32_e32 v122, v124
	v_mov_b32_e32 v123, v128
	v_pk_fma_f32 v[40:41], v[152:153], v[120:121], v[50:51]
	v_add_f32_e32 v12, v12, v19
	v_pk_fma_f32 v[18:19], v[154:155], v[20:21], v[30:31]
	v_add_f32_e32 v62, v22, v23
	v_pk_fma_f32 v[20:21], v[154:155], v[36:37], v[44:45]
	v_pk_fma_f32 v[22:23], v[154:155], v[52:53], v[46:47]
	v_add_f32_e32 v46, v28, v29
	v_add_f32_e32 v47, v34, v35
	v_pk_fma_f32 v[28:29], v[154:155], v[84:85], v[54:55]
	v_pk_fma_f32 v[30:31], v[154:155], v[100:101], v[56:57]
	v_pk_fma_f32 v[34:35], v[154:155], v[116:117], v[60:61]
	v_mov_b32_e32 v37, v134
	v_mov_b32_e32 v134, v131
	v_add_f32_e32 v24, 0, v24
	v_pk_mul_f32 v[50:51], v[156:157], v[78:79]
	v_add_f32_e32 v38, 0, v38
	v_add_f32_e32 v40, 0, v40
	v_mov_b32_e32 v36, v130
	v_pk_fma_f32 v[18:19], v[158:159], v[26:27], v[18:19]
	v_pk_fma_f32 v[26:27], v[158:159], v[90:91], v[28:29]
	v_pk_fma_f32 v[28:29], v[158:159], v[106:107], v[30:31]
	v_pk_fma_f32 v[30:31], v[158:159], v[122:123], v[34:35]
	v_pk_mul_f32 v[34:35], v[146:147], v[134:135]
	v_add_f32_e32 v63, v24, v25
	v_pk_fma_f32 v[24:25], v[154:155], v[68:69], v[50:51]
	v_add_f32_e32 v50, v38, v39
	v_add_f32_e32 v51, v40, v41
	v_mov_b32_e32 v38, v132
	v_mov_b32_e32 v39, v136
	v_mov_b32_e32 v41, v142
	v_mov_b32_e32 v142, v139
	v_pk_fma_f32 v[18:19], v[160:161], v[32:33], v[18:19]
	v_pk_fma_f32 v[14:15], v[14:15], v[36:37], v[34:35]
	v_mov_b32_e32 v136, v133
	v_mov_b32_e32 v40, v138
	v_pk_fma_f32 v[20:21], v[158:159], v[42:43], v[20:21]
	v_pk_mul_f32 v[42:43], v[156:157], v[142:143]
	v_add_f32_e32 v12, v12, v18
	v_pk_fma_f32 v[14:15], v[150:151], v[38:39], v[14:15]
	v_mov_b32_e32 v44, v140
	v_mov_b32_e32 v45, v144
	v_pk_fma_f32 v[20:21], v[160:161], v[48:49], v[20:21]
	v_pk_fma_f32 v[32:33], v[154:155], v[40:41], v[42:43]
	v_add_f32_e32 v12, v12, v19
	v_pk_fma_f32 v[14:15], v[152:153], v[136:137], v[14:15]
	v_mov_b32_e32 v144, v141
	v_pk_fma_f32 v[22:23], v[158:159], v[58:59], v[22:23]
	v_add_f32_e32 v18, v62, v20
	v_pk_fma_f32 v[32:33], v[158:159], v[44:45], v[32:33]
	v_mul_f32_e32 v1, v1, v12
	v_add_f32_e32 v12, 0, v14
	v_mov_b32_e32 v128, v125
	v_pk_fma_f32 v[24:25], v[158:159], v[74:75], v[24:25]
	v_pk_fma_f32 v[22:23], v[160:161], v[64:65], v[22:23]
	v_add_f32_e32 v21, v18, v21
	v_pk_fma_f32 v[18:19], v[160:161], v[144:145], v[32:33]
	v_add_f32_e32 v12, v12, v15
	v_pk_fma_f32 v[24:25], v[160:161], v[80:81], v[24:25]
	v_pk_fma_f32 v[26:27], v[160:161], v[96:97], v[26:27]
	v_pk_fma_f32 v[28:29], v[160:161], v[112:113], v[28:29]
	v_pk_fma_f32 v[30:31], v[160:161], v[128:129], v[30:31]
	v_add_f32_e32 v20, v63, v22
	v_add_f32_e32 v12, v12, v18
	v_add_f32_e32 v22, v46, v24
	v_add_f32_e32 v24, v47, v26
	v_add_f32_e32 v26, v50, v28
	v_add_f32_e32 v28, v51, v30
	v_add_f32_e32 v20, v20, v23
	v_add_f32_e32 v12, v12, v19
	v_add_f32_e32 v22, v22, v25
	v_add_f32_e32 v23, v24, v27
	v_add_f32_e32 v24, v26, v29
	v_add_f32_e32 v25, v28, v31
	v_mul_f32_e32 v2, v2, v21
	v_mul_f32_e32 v3, v3, v20
	v_mul_f32_e32 v0, v0, v12
	v_mul_f32_e32 v4, v4, v22
	v_mul_f32_e32 v5, v5, v23
	v_mul_f32_e32 v6, v6, v24
	v_mul_f32_e32 v7, v7, v25
	v_cvt_pk_bf16_f32 v0, v0, v1
	v_cvt_pk_bf16_f32 v1, v2, v3
	v_cvt_pk_bf16_f32 v2, v4, v5
	v_cvt_pk_bf16_f32 v3, v6, v7
	flat_store_dwordx4 v[148:149], v[0:3] sc1
	s_andn2_b64 exec, exec, s[20:21]
	s_cbranch_execnz .LBB0_310
